# plus: conversion tiles prefetch all 4 row-block loads up front; MLA-prep items moved to blocks with short FOX items; phase-4 blocks get one NSA and one MLA item each
# speedup vs baseline: 1.6885x; 1.0252x over previous
; DI int TID() { int t = threadIdx.x; asm volatile("" : "+v"(t)); return t; }
; template <bool MAP = false>
; DI void conv_tile(const float* __restrict__ src, int N, int K, bfu* __restrict__ dst, const float* __restrict__ g,
;                   int tk, int tn, char* smem, int ldk = -1) {
;   const int LK = ldk < 0 ? K : ldk;
;   float* T = (float*)smem;
;   const int tid = TID();
;   __syncthreads();
; #pragma unroll
;   for (int j = 0; j < 4; ++j) {
;     int k = (tid >> 4) + 16 * j, n4 = (tid & 15) * 4;
;     int gn = tn * 64 + n4, gk = tk * 64 + k;
;     float4 v = make_float4(0.f, 0.f, 0.f, 0.f);
;     const int og = MAP ? in_colmap(gn) : (gn < N ? gn : -1);
;     if (og >= 0) v = *(const float4*)(src + (size_t)gk * N + og);
;     float gg = g ? g[gk] : 1.f;
;     T[k * 65 + n4 + 0] = v.x * gg; T[k * 65 + n4 + 1] = v.y * gg; T[k * 65 + n4 + 2] = v.z * gg; T[k * 65 + n4 + 3] = v.w * gg;
;   }
;   __syncthreads();
; DI void conv_item_B(const Params& p, int L, int it, char* smem) {
;     ...
;   else if (it < 52) { int t = it - 36; conv_tile(p.mla_w_ukv + (size_t)L * 128 * 512, 512, 128, p.wt_ukv, p.mla_ckv_g + L * 128, t / 8, t % 8, smem); }
.LBB0_47:
	s_add_i32 s2, s6, 0xfffff91c
	v_mov_b32_e32 v11, v224
	s_lshl_b32 s3, s2, 6
	v_lshlrev_b32_e32 v0, 2, v11
	s_lshl_b32 s2, s2, 3
	v_ashrrev_i32_e32 v13, 4, v11
	v_and_b32_e32 v14, 60, v0
	s_and_b32 s4, s3, 0x1c0
	s_and_b32 s5, s2, 0x7fffffc0
	v_or_b32_e32 v0, s4, v14
	v_add_u32_e32 v8, s5, v13
	v_lshlrev_b32_e32 v188, 2, v0
	v_ashrrev_i32_e32 v9, 31, v8
	v_lshl_add_u64 v[6:7], s[10:11], 0, v[188:189]
	v_lshlrev_b64 v[0:1], 11, v[8:9]
	v_lshl_add_u64 v[0:1], v[6:7], 0, v[0:1]
	s_barrier
	v_add_u32_e32 v210, 16, v8
	v_ashrrev_i32_e32 v211, 31, v210
	v_lshlrev_b64 v[210:211], 11, v[210:211]
	v_lshl_add_u64 v[210:211], v[6:7], 0, v[210:211]
	global_load_dwordx4 v[240:243], v[210:211], off
	v_add_u32_e32 v210, 32, v8
	v_ashrrev_i32_e32 v211, 31, v210
	v_lshlrev_b64 v[210:211], 11, v[210:211]
	v_lshl_add_u64 v[210:211], v[6:7], 0, v[210:211]
	global_load_dwordx4 v[244:247], v[210:211], off
	v_add_u32_e32 v210, 48, v8
	v_ashrrev_i32_e32 v211, 31, v210
	v_lshlrev_b64 v[210:211], 11, v[210:211]
	v_lshl_add_u64 v[210:211], v[6:7], 0, v[210:211]
	global_load_dwordx4 v[248:251], v[210:211], off
	global_load_dwordx4 v[0:3], v[0:1], off
	v_readlane_b32 s16, v254, 42
	v_readlane_b32 s17, v254, 43
	v_mov_b32_e32 v10, 1.0
	s_andn2_b64 vcc, exec, s[16:17]
	v_cndmask_b32_e64 v4, 0, 1, s[16:17]
	v_cmp_ne_u32_e64 s[2:3], 1, v4
	v_lshl_add_u64 v[4:5], v[8:9], 2, s[14:15]
	v_mov_b32_e32 v12, 1.0
	s_cbranch_vccnz .LBB0_49
	global_load_dword v12, v[4:5], off

; DI void phase_attn1(const Params& p, int L, char* smem) {
;   const int extra = (L > 0) ? CV_NC : 0;
;   for (int it = blockIdx.x; it < 1792 + extra; it += gridDim.x) {
;     if (it < 512) attn_item<2>(p, it, smem);
;     else if (it < 1024) nsacmp_item(p, L, it - 512, smem);
;     else if (it < 1536) attn_item<0>(p, it - 1024, smem);
;     else if (it < 1792) mlaprep_item(p, L, it - 1536, smem);
;     else conv_item_C(p, L, it - 1792, smem);
;   }
.LBB0_150:
	v_readlane_b32 s2, v254, 38
	v_readlane_b32 s3, v254, 39
	s_load_dword s2, s[2:3], 0x0
	v_readlane_b32 s33, v255, 62
	s_max_i32 s3, s60, 0x800
	s_waitcnt lgkmcnt(0)
	s_add_i32 s33, s2, s33
	s_cmp_ge_i32 s33, s3
	s_cbranch_scc1 .LBB0_484
.LBB0_151:
	v_writelane_b32 v255, s33, 62
	s_lshr_b32 s2, s33, 9
	s_cmp_eq_u32 s2, 3
	s_cbranch_scc0 .Lp3_noswap
	s_xor_b32 s33, s33, 0x100
	s_cmpk_eq_i32 s60, 0x700
	s_cbranch_scc0 .Lp3_noswap
	s_cmpk_ge_i32 s33, 0x700
	s_cbranch_scc1 .LBB0_150

; DI int TID() { int t = threadIdx.x; asm volatile("" : "+v"(t)); return t; }
; DI unsigned pk2(float a, float b) { f32x2_t v = {a, b}; bf16x2_t r_ = __builtin_convertvector(v, bf16x2_t); return __builtin_bit_cast(unsigned, r_); }
; template <bool MAP = false>
; DI void conv_tile(const float* __restrict__ src, int N, int K, bfu* __restrict__ dst, const float* __restrict__ g,
;                   int tk, int tn, char* smem, int ldk = -1) {
;   const int LK = ldk < 0 ? K : ldk;
;   float* T = (float*)smem;
;   const int tid = TID();
;   __syncthreads();
; #pragma unroll
;   for (int j = 0; j < 4; ++j) {
;     int k = (tid >> 4) + 16 * j, n4 = (tid & 15) * 4;
;     int gn = tn * 64 + n4, gk = tk * 64 + k;
;     float4 v = make_float4(0.f, 0.f, 0.f, 0.f);
;     const int og = MAP ? in_colmap(gn) : (gn < N ? gn : -1);
;     if (og >= 0) v = *(const float4*)(src + (size_t)gk * N + og);
;     float gg = g ? g[gk] : 1.f;
;     T[k * 65 + n4 + 0] = v.x * gg; T[k * 65 + n4 + 1] = v.y * gg; T[k * 65 + n4 + 2] = v.z * gg; T[k * 65 + n4 + 3] = v.w * gg;
;   }
;   __syncthreads();
; #pragma unroll
;   for (int j = 0; j < 2; ++j) {
;     int n = (tid >> 3) + 32 * j, kc = tid & 7;
;     float e[8];
; #pragma unroll
;     for (int q = 0; q < 8; ++q) e[q] = T[(kc * 8 + q) * 65 + n];
;     u32x4 o = {pk2(e[0], e[1]), pk2(e[2], e[3]), pk2(e[4], e[5]), pk2(e[6], e[7])};
;     *(u32x4*)(dst + (size_t)(tn * 64 + n) * LK + tk * 64 + kc * 8) = o;
;   }
; }
; DI void conv_item_C(const Params& p, int L, int it, char* smem) {
;     ...
;   else if (it < 2880) { int t = it - 2816; conv_tile(p.w_ple_proj + (size_t)L * 256 * D, D, 256, p.wt_pp, nullptr, t / 16, t % 16, smem); }
.LBB0_162:
	s_andn2_b64 vcc, exec, s[2:3]
	s_cbranch_vccnz .LBB0_164
	v_mov_b32_e32 v8, v224
	s_lshl_b32 s3, s6, 2
	s_lshl_b32 s2, s6, 6
	v_lshlrev_b32_e32 v0, 2, v8
	s_and_b32 s3, s3, 0x3fc0
	v_ashrrev_i32_e32 v2, 4, v8
	v_and_b32_e32 v3, 60, v0
	s_and_b32 s2, s2, 0x3c0
	s_add_i32 s96, s3, 0xffffd400
	v_or_b32_e32 v0, s2, v3
	v_add_u32_e32 v6, s96, v2
	v_lshlrev_b32_e32 v188, 2, v0
	v_ashrrev_i32_e32 v7, 31, v6
	v_lshl_add_u64 v[4:5], s[64:65], 0, v[188:189]
	v_lshlrev_b64 v[0:1], 12, v[6:7]
	s_movk_i32 s3, 0x104
	v_lshl_add_u64 v[0:1], v[4:5], 0, v[0:1]
	v_mul_lo_u32 v2, v2, s3
	s_waitcnt vmcnt(63) expcnt(7) lgkmcnt(15)
	s_barrier
	v_lshl_add_u32 v7, v3, 2, v2
	v_add_u32_e32 v210, 16, v6
	v_ashrrev_i32_e32 v211, 31, v210
	v_lshlrev_b64 v[210:211], 12, v[210:211]
	v_lshl_add_u64 v[210:211], v[4:5], 0, v[210:211]
	global_load_dwordx4 v[240:243], v[210:211], off
	v_add_u32_e32 v210, 32, v6
	v_ashrrev_i32_e32 v211, 31, v210
	v_lshlrev_b64 v[210:211], 12, v[210:211]
	v_lshl_add_u64 v[210:211], v[4:5], 0, v[210:211]
	global_load_dwordx4 v[244:247], v[210:211], off
	v_add_u32_e32 v210, 48, v6
	v_ashrrev_i32_e32 v211, 31, v210
	v_lshlrev_b64 v[210:211], 12, v[210:211]
	v_lshl_add_u64 v[210:211], v[4:5], 0, v[210:211]
	global_load_dwordx4 v[248:251], v[210:211], off
	global_load_dwordx4 v[0:3], v[0:1], off
	v_add_u32_e32 v9, 0x1040, v7
	v_ashrrev_i32_e32 v22, 3, v8
	v_readlane_b32 s16, v253, 48
	s_lshl_b64 s[4:5], s[96:97], 1
	v_readlane_b32 s30, v253, 62
	v_readlane_b32 s31, v253, 63
	s_add_u32 s4, s30, s4
	s_addc_u32 s5, s31, s5
	v_readlane_b32 s17, v253, 49
	v_readlane_b32 s18, v253, 50
	v_readlane_b32 s19, v253, 51
	v_readlane_b32 s20, v253, 52
	v_readlane_b32 s21, v253, 53
	v_readlane_b32 s22, v253, 54
	v_readlane_b32 s23, v253, 55
	v_readlane_b32 s24, v253, 56
	v_readlane_b32 s25, v253, 57
	v_readlane_b32 s26, v253, 58
	v_readlane_b32 s27, v253, 59
	v_readlane_b32 s28, v253, 60
	v_readlane_b32 s29, v253, 61
	s_waitcnt vmcnt(0)
	ds_write2_b32 v7, v0, v1 offset1:1
	ds_write2_b32 v7, v2, v3 offset0:2 offset1:3
	v_add_u32_e32 v0, 16, v6
	v_ashrrev_i32_e32 v1, 31, v0
	v_lshlrev_b64 v[0:1], 12, v[0:1]
	v_lshl_add_u64 v[0:1], v[4:5], 0, v[0:1]
	global_load_dwordx4 v[0:3], v[0:1], off
	s_waitcnt vmcnt(0)
	ds_write2_b32 v9, v0, v1 offset1:1
	v_add_u32_e32 v0, 0x1048, v7
	ds_write2_b32 v0, v2, v3 offset1:1
	v_add_u32_e32 v0, 32, v6
	v_ashrrev_i32_e32 v1, 31, v0
	v_lshlrev_b64 v[0:1], 12, v[0:1]
	v_lshl_add_u64 v[0:1], v[4:5], 0, v[0:1]
	global_load_dwordx4 v[0:3], v[0:1], off
	v_add_u32_e32 v9, 0x2080, v7
	s_waitcnt vmcnt(0)
	ds_write2_b32 v9, v0, v1 offset1:1
	v_add_u32_e32 v0, 0x2088, v7
	ds_write2_b32 v0, v2, v3 offset1:1
	v_add_u32_e32 v0, 48, v6
	v_ashrrev_i32_e32 v1, 31, v0
	v_lshlrev_b64 v[0:1], 12, v[0:1]
	v_lshl_add_u64 v[0:1], v[4:5], 0, v[0:1]
	global_load_dwordx4 v[0:3], v[0:1], off
	v_add_u32_e32 v4, 0x30c0, v7
	s_waitcnt vmcnt(0)
	ds_write2_b32 v4, v0, v1 offset1:1
	v_add_u32_e32 v0, 0x30c8, v7
	ds_write2_b32 v0, v2, v3 offset1:1
	v_lshlrev_b32_e32 v0, 3, v8
	v_and_b32_e32 v2, 56, v0
	v_lshlrev_b32_e32 v188, 1, v2
	v_mul_u32_u24_e32 v2, 0x104, v2
	v_lshl_add_u32 v2, v22, 2, v2
	s_waitcnt lgkmcnt(0)
	s_barrier
	ds_read2_b32 v[6:7], v2 offset1:32
	ds_read2_b32 v[8:9], v2 offset0:65 offset1:97
	ds_read2_b32 v[10:11], v2 offset0:130 offset1:162
	ds_read2_b32 v[12:13], v2 offset0:195 offset1:227
	v_add_u32_e32 v2, 0x400, v2
	ds_read2_b32 v[14:15], v2 offset0:4 offset1:36
	ds_read2_b32 v[16:17], v2 offset0:69 offset1:101
	ds_read2_b32 v[18:19], v2 offset0:134 offset1:166
	ds_read2_b32 v[20:21], v2 offset0:199 offset1:231
	v_add_u32_e32 v22, s2, v22
	v_ashrrev_i32_e32 v23, 31, v22
	v_lshl_add_u64 v[0:1], s[4:5], 0, v[188:189]
	v_lshlrev_b64 v[24:25], 9, v[22:23]
	s_waitcnt lgkmcnt(6)
	v_cvt_pk_bf16_f32 v2, v6, v8
	s_waitcnt lgkmcnt(4)
	v_cvt_pk_bf16_f32 v3, v10, v12
	s_waitcnt lgkmcnt(2)
	v_cvt_pk_bf16_f32 v4, v14, v16
	s_waitcnt lgkmcnt(0)
	v_cvt_pk_bf16_f32 v5, v18, v20
	v_lshl_add_u64 v[24:25], v[0:1], 0, v[24:25]
	v_add_u32_e32 v6, 32, v22
	global_store_dwordx4 v[24:25], v[2:5], off
	s_nop 1
	v_cvt_pk_bf16_f32 v2, v7, v9
	v_ashrrev_i32_e32 v7, 31, v6
	v_lshlrev_b64 v[6:7], 9, v[6:7]
	v_cvt_pk_bf16_f32 v3, v11, v13
	v_cvt_pk_bf16_f32 v4, v15, v17
	v_cvt_pk_bf16_f32 v5, v19, v21
	v_lshl_add_u64 v[0:1], v[0:1], 0, v[6:7]
	global_store_dwordx4 v[0:1], v[2:5], off

; DI int TID() { int t = threadIdx.x; asm volatile("" : "+v"(t)); return t; }
; template <bool MAP = false>
; DI void conv_tile(const float* __restrict__ src, int N, int K, bfu* __restrict__ dst, const float* __restrict__ g,
;                   int tk, int tn, char* smem, int ldk = -1) {
;   const int LK = ldk < 0 ? K : ldk;
;   float* T = (float*)smem;
;   const int tid = TID();
;   __syncthreads();
; #pragma unroll
;   for (int j = 0; j < 4; ++j) {
;     int k = (tid >> 4) + 16 * j, n4 = (tid & 15) * 4;
;     int gn = tn * 64 + n4, gk = tk * 64 + k;
;     float4 v = make_float4(0.f, 0.f, 0.f, 0.f);
;     const int og = MAP ? in_colmap(gn) : (gn < N ? gn : -1);
;     if (og >= 0) v = *(const float4*)(src + (size_t)gk * N + og);
;     float gg = g ? g[gk] : 1.f;
;     T[k * 65 + n4 + 0] = v.x * gg; T[k * 65 + n4 + 1] = v.y * gg; T[k * 65 + n4 + 2] = v.z * gg; T[k * 65 + n4 + 3] = v.w * gg;
;   }
;   __syncthreads();
; DI void conv_item_C(const Params& p, int L, int it, char* smem) {
;     ...
;   else if (it < 2816) { int t = it - 2560; conv_tile(p.w_ple_gate + (size_t)L * D * D, D, D, p.wt_pg, p.norm_ple_g + L * D, t / 16, t % 16, smem); }
.LBB0_165:
	s_andn2_b64 vcc, exec, s[2:3]
	s_cbranch_vccnz .LBB0_175
	s_lshl_b32 s2, s6, 6
	v_mov_b32_e32 v11, v224
	s_and_b32 s4, s2, 0x3c0
	s_lshl_b32 s2, s6, 2
	s_and_b32 s2, s2, 0x3fc0
	v_lshlrev_b32_e32 v0, 2, v11
	v_ashrrev_i32_e32 v13, 4, v11
	v_and_b32_e32 v14, 60, v0
	s_add_i32 s96, s2, 0xffffd800
	v_or_b32_e32 v0, s4, v14
	v_add_u32_e32 v8, s96, v13
	v_lshlrev_b32_e32 v188, 2, v0
	v_ashrrev_i32_e32 v9, 31, v8
	v_lshl_add_u64 v[6:7], s[66:67], 0, v[188:189]
	v_lshlrev_b64 v[0:1], 12, v[8:9]
	v_lshl_add_u64 v[0:1], v[6:7], 0, v[0:1]
	s_waitcnt vmcnt(63) expcnt(7) lgkmcnt(15)
	s_barrier
	v_add_u32_e32 v210, 16, v8
	v_ashrrev_i32_e32 v211, 31, v210
	v_lshlrev_b64 v[210:211], 12, v[210:211]
	v_lshl_add_u64 v[210:211], v[6:7], 0, v[210:211]
	global_load_dwordx4 v[240:243], v[210:211], off
	v_add_u32_e32 v210, 32, v8
	v_ashrrev_i32_e32 v211, 31, v210
	v_lshlrev_b64 v[210:211], 12, v[210:211]
	v_lshl_add_u64 v[210:211], v[6:7], 0, v[210:211]
	global_load_dwordx4 v[244:247], v[210:211], off
	v_add_u32_e32 v210, 48, v8
	v_ashrrev_i32_e32 v211, 31, v210
	v_lshlrev_b64 v[210:211], 12, v[210:211]
	v_lshl_add_u64 v[210:211], v[6:7], 0, v[210:211]
	global_load_dwordx4 v[248:251], v[210:211], off
	global_load_dwordx4 v[0:3], v[0:1], off
	v_readlane_b32 s8, v255, 4
	v_readlane_b32 s9, v255, 5
	v_mov_b32_e32 v10, 1.0
	s_andn2_b64 vcc, exec, s[8:9]
	v_cndmask_b32_e64 v4, 0, 1, s[8:9]
	v_cmp_ne_u32_e64 s[2:3], 1, v4
	v_lshl_add_u64 v[4:5], v[8:9], 2, s[86:87]
	v_mov_b32_e32 v12, 1.0
	s_cbranch_vccnz .LBB0_168
	global_load_dword v12, v[4:5], off

; DI int TID() { int t = threadIdx.x; asm volatile("" : "+v"(t)); return t; }
; DI unsigned pk2(float a, float b) { f32x2_t v = {a, b}; bf16x2_t r_ = __builtin_convertvector(v, bf16x2_t); return __builtin_bit_cast(unsigned, r_); }
; template <bool MAP = false>
; DI void conv_tile(const float* __restrict__ src, int N, int K, bfu* __restrict__ dst, const float* __restrict__ g,
;                   int tk, int tn, char* smem, int ldk = -1) {
;   const int LK = ldk < 0 ? K : ldk;
;   float* T = (float*)smem;
;   const int tid = TID();
;   __syncthreads();
; #pragma unroll
;   for (int j = 0; j < 4; ++j) {
;     int k = (tid >> 4) + 16 * j, n4 = (tid & 15) * 4;
;     int gn = tn * 64 + n4, gk = tk * 64 + k;
;     float4 v = make_float4(0.f, 0.f, 0.f, 0.f);
;     const int og = MAP ? in_colmap(gn) : (gn < N ? gn : -1);
;     if (og >= 0) v = *(const float4*)(src + (size_t)gk * N + og);
;     float gg = g ? g[gk] : 1.f;
;     T[k * 65 + n4 + 0] = v.x * gg; T[k * 65 + n4 + 1] = v.y * gg; T[k * 65 + n4 + 2] = v.z * gg; T[k * 65 + n4 + 3] = v.w * gg;
;   }
;   __syncthreads();
; #pragma unroll
;   for (int j = 0; j < 2; ++j) {
;     int n = (tid >> 3) + 32 * j, kc = tid & 7;
;     float e[8];
; #pragma unroll
;     for (int q = 0; q < 8; ++q) e[q] = T[(kc * 8 + q) * 65 + n];
;     u32x4 o = {pk2(e[0], e[1]), pk2(e[2], e[3]), pk2(e[4], e[5]), pk2(e[6], e[7])};
;     *(u32x4*)(dst + (size_t)(tn * 64 + n) * LK + tk * 64 + kc * 8) = o;
;   }
; }
; DI void conv_item_C(const Params& p, int L, int it, char* smem) {
;     ...
;   else if (it < 2560) { int t = it - 1536; conv_tile(p.w_down + (size_t)L * DFF * D, D, DFF, p.wt_down, nullptr, t / 16, t % 16, smem); }
.LBB0_176:
	s_andn2_b64 vcc, exec, s[2:3]
	s_cbranch_vccnz .LBB0_178
	v_mov_b32_e32 v8, v224
	s_lshl_b32 s3, s6, 2
	s_lshl_b32 s2, s6, 6
	v_lshlrev_b32_e32 v0, 2, v8
	s_and_b32 s3, s3, 0x3fc0
	v_ashrrev_i32_e32 v2, 4, v8
	v_and_b32_e32 v3, 60, v0
	s_and_b32 s2, s2, 0x3c0
	s_add_i32 s96, s3, 0xffffe800
	v_or_b32_e32 v0, s2, v3
	v_add_u32_e32 v6, s96, v2
	v_lshlrev_b32_e32 v188, 2, v0
	v_ashrrev_i32_e32 v7, 31, v6
	v_lshl_add_u64 v[4:5], s[90:91], 0, v[188:189]
	v_lshlrev_b64 v[0:1], 12, v[6:7]
	s_movk_i32 s3, 0x104
	v_lshl_add_u64 v[0:1], v[4:5], 0, v[0:1]
	v_mul_lo_u32 v2, v2, s3
	s_waitcnt vmcnt(63) expcnt(7) lgkmcnt(15)
	s_barrier
	v_lshl_add_u32 v7, v3, 2, v2
	v_add_u32_e32 v210, 16, v6
	v_ashrrev_i32_e32 v211, 31, v210
	v_lshlrev_b64 v[210:211], 12, v[210:211]
	v_lshl_add_u64 v[210:211], v[4:5], 0, v[210:211]
	global_load_dwordx4 v[240:243], v[210:211], off
	v_add_u32_e32 v210, 32, v6
	v_ashrrev_i32_e32 v211, 31, v210
	v_lshlrev_b64 v[210:211], 12, v[210:211]
	v_lshl_add_u64 v[210:211], v[4:5], 0, v[210:211]
	global_load_dwordx4 v[244:247], v[210:211], off
	v_add_u32_e32 v210, 48, v6
	v_ashrrev_i32_e32 v211, 31, v210
	v_lshlrev_b64 v[210:211], 12, v[210:211]
	v_lshl_add_u64 v[210:211], v[4:5], 0, v[210:211]
	global_load_dwordx4 v[248:251], v[210:211], off
	global_load_dwordx4 v[0:3], v[0:1], off
	v_add_u32_e32 v9, 0x1040, v7
	v_ashrrev_i32_e32 v22, 3, v8
	v_readlane_b32 s16, v253, 48
	s_lshl_b64 s[4:5], s[96:97], 1
	v_readlane_b32 s26, v253, 58
	v_readlane_b32 s27, v253, 59
	s_add_u32 s4, s26, s4
	s_addc_u32 s5, s27, s5
	v_readlane_b32 s17, v253, 49
	v_readlane_b32 s18, v253, 50
	v_readlane_b32 s19, v253, 51
	v_readlane_b32 s20, v253, 52
	v_readlane_b32 s21, v253, 53
	v_readlane_b32 s22, v253, 54
	v_readlane_b32 s23, v253, 55
	v_readlane_b32 s24, v253, 56
	v_readlane_b32 s25, v253, 57
	v_readlane_b32 s28, v253, 60
	v_readlane_b32 s29, v253, 61
	v_readlane_b32 s30, v253, 62
	v_readlane_b32 s31, v253, 63
	s_waitcnt vmcnt(0)
	ds_write2_b32 v7, v0, v1 offset1:1
	ds_write2_b32 v7, v2, v3 offset0:2 offset1:3
	v_add_u32_e32 v0, 16, v6
	v_ashrrev_i32_e32 v1, 31, v0
	v_lshlrev_b64 v[0:1], 12, v[0:1]
	v_lshl_add_u64 v[0:1], v[4:5], 0, v[0:1]
	global_load_dwordx4 v[0:3], v[0:1], off
	s_waitcnt vmcnt(0)
	ds_write2_b32 v9, v0, v1 offset1:1
	v_add_u32_e32 v0, 0x1048, v7
	ds_write2_b32 v0, v2, v3 offset1:1
	v_add_u32_e32 v0, 32, v6
	v_ashrrev_i32_e32 v1, 31, v0
	v_lshlrev_b64 v[0:1], 12, v[0:1]
	v_lshl_add_u64 v[0:1], v[4:5], 0, v[0:1]
	global_load_dwordx4 v[0:3], v[0:1], off
	v_add_u32_e32 v9, 0x2080, v7
	s_waitcnt vmcnt(0)
	ds_write2_b32 v9, v0, v1 offset1:1
	v_add_u32_e32 v0, 0x2088, v7
	ds_write2_b32 v0, v2, v3 offset1:1
	v_add_u32_e32 v0, 48, v6
	v_ashrrev_i32_e32 v1, 31, v0
	v_lshlrev_b64 v[0:1], 12, v[0:1]
	v_lshl_add_u64 v[0:1], v[4:5], 0, v[0:1]
	global_load_dwordx4 v[0:3], v[0:1], off
	v_add_u32_e32 v4, 0x30c0, v7
	s_waitcnt vmcnt(0)
	ds_write2_b32 v4, v0, v1 offset1:1
	v_add_u32_e32 v0, 0x30c8, v7
	ds_write2_b32 v0, v2, v3 offset1:1
	v_lshlrev_b32_e32 v0, 3, v8
	v_and_b32_e32 v2, 56, v0
	v_lshlrev_b32_e32 v188, 1, v2
	v_mul_u32_u24_e32 v2, 0x104, v2
	v_lshl_add_u32 v2, v22, 2, v2
	s_waitcnt lgkmcnt(0)
	s_barrier
	ds_read2_b32 v[6:7], v2 offset1:32
	ds_read2_b32 v[8:9], v2 offset0:65 offset1:97
	ds_read2_b32 v[10:11], v2 offset0:130 offset1:162
	ds_read2_b32 v[12:13], v2 offset0:195 offset1:227
	v_add_u32_e32 v2, 0x400, v2
	ds_read2_b32 v[14:15], v2 offset0:4 offset1:36
	ds_read2_b32 v[16:17], v2 offset0:69 offset1:101
	ds_read2_b32 v[18:19], v2 offset0:134 offset1:166
	ds_read2_b32 v[20:21], v2 offset0:199 offset1:231
	v_add_u32_e32 v22, s2, v22
	v_ashrrev_i32_e32 v23, 31, v22
	v_lshl_add_u64 v[0:1], s[4:5], 0, v[188:189]
	v_lshlrev_b64 v[24:25], 13, v[22:23]
	s_waitcnt lgkmcnt(6)
	v_cvt_pk_bf16_f32 v2, v6, v8
	s_waitcnt lgkmcnt(4)
	v_cvt_pk_bf16_f32 v3, v10, v12
	s_waitcnt lgkmcnt(2)
	v_cvt_pk_bf16_f32 v4, v14, v16
	s_waitcnt lgkmcnt(0)
	v_cvt_pk_bf16_f32 v5, v18, v20
	v_lshl_add_u64 v[24:25], v[0:1], 0, v[24:25]
	v_add_u32_e32 v6, 32, v22
	global_store_dwordx4 v[24:25], v[2:5], off
	s_nop 1
	v_cvt_pk_bf16_f32 v2, v7, v9
	v_ashrrev_i32_e32 v7, 31, v6
	v_lshlrev_b64 v[6:7], 13, v[6:7]
	v_cvt_pk_bf16_f32 v3, v11, v13
	v_cvt_pk_bf16_f32 v4, v15, v17
	v_cvt_pk_bf16_f32 v5, v19, v21
	v_lshl_add_u64 v[0:1], v[0:1], 0, v[6:7]
	global_store_dwordx4 v[0:1], v[2:5], off

; DI int TID() { int t = threadIdx.x; asm volatile("" : "+v"(t)); return t; }
; template <bool MAP = false>
; DI void conv_tile(const float* __restrict__ src, int N, int K, bfu* __restrict__ dst, const float* __restrict__ g,
;                   int tk, int tn, char* smem, int ldk = -1) {
;   const int LK = ldk < 0 ? K : ldk;
;   float* T = (float*)smem;
;   const int tid = TID();
;   __syncthreads();
; #pragma unroll
;   for (int j = 0; j < 4; ++j) {
;     int k = (tid >> 4) + 16 * j, n4 = (tid & 15) * 4;
;     int gn = tn * 64 + n4, gk = tk * 64 + k;
;     float4 v = make_float4(0.f, 0.f, 0.f, 0.f);
;     const int og = MAP ? in_colmap(gn) : (gn < N ? gn : -1);
;     if (og >= 0) v = *(const float4*)(src + (size_t)gk * N + og);
;     float gg = g ? g[gk] : 1.f;
;     T[k * 65 + n4 + 0] = v.x * gg; T[k * 65 + n4 + 1] = v.y * gg; T[k * 65 + n4 + 2] = v.z * gg; T[k * 65 + n4 + 3] = v.w * gg;
;   }
;   __syncthreads();
; DI void conv_item_C(const Params& p, int L, int it, char* smem) {
;     ...
;   else if (it < 1536) { int t = it - 512; conv_tile(p.w_up + (size_t)L * D * DFF, DFF, D, p.wt_up, p.norm_mlp_g + L * D, t / 64, t % 64, smem); }
.LBB0_179:
	s_andn2_b64 vcc, exec, s[2:3]
	s_cbranch_vccnz .LBB0_189
	v_mov_b32_e32 v11, v224
	s_and_b32 s4, s6, 0x7c0
	s_lshl_b32 s2, s6, 6
	v_lshlrev_b32_e32 v0, 2, v11
	s_add_i32 s96, s4, 0xfffffe00
	v_ashrrev_i32_e32 v8, 4, v11
	v_and_b32_e32 v13, 60, v0
	s_and_b32 s7, s2, 0xfc0
	v_or_b32_e32 v0, s7, v13
	v_add_u32_e32 v6, s96, v8
	v_lshlrev_b32_e32 v188, 2, v0
	v_ashrrev_i32_e32 v7, 31, v6
	v_lshl_add_u64 v[4:5], s[92:93], 0, v[188:189]
	v_lshlrev_b64 v[0:1], 14, v[6:7]
	v_lshl_add_u64 v[0:1], v[4:5], 0, v[0:1]
	s_waitcnt vmcnt(63) expcnt(7) lgkmcnt(15)
	s_barrier
	v_add_u32_e32 v210, 16, v6
	v_ashrrev_i32_e32 v211, 31, v210
	v_lshlrev_b64 v[210:211], 14, v[210:211]
	v_lshl_add_u64 v[210:211], v[4:5], 0, v[210:211]
	global_load_dwordx4 v[240:243], v[210:211], off
	v_add_u32_e32 v210, 32, v6
	v_ashrrev_i32_e32 v211, 31, v210
	v_lshlrev_b64 v[210:211], 14, v[210:211]
	v_lshl_add_u64 v[210:211], v[4:5], 0, v[210:211]
	global_load_dwordx4 v[244:247], v[210:211], off
	v_add_u32_e32 v210, 48, v6
	v_ashrrev_i32_e32 v211, 31, v210
	v_lshlrev_b64 v[210:211], 14, v[210:211]
	v_lshl_add_u64 v[210:211], v[4:5], 0, v[210:211]
	global_load_dwordx4 v[248:251], v[210:211], off
	global_load_dwordx4 v[0:3], v[0:1], off
	v_readlane_b32 s8, v255, 6
	v_readlane_b32 s9, v255, 7
	v_mov_b32_e32 v10, 1.0
	s_andn2_b64 vcc, exec, s[8:9]
	v_cndmask_b32_e64 v9, 0, 1, s[8:9]
	v_cmp_ne_u32_e64 s[2:3], 1, v9
	v_mov_b32_e32 v12, 1.0
	s_cbranch_vccnz .LBB0_182
	v_ashrrev_i32_e32 v9, 31, v8
	s_mov_b32 s5, s97
	v_lshl_add_u64 v[14:15], v[8:9], 0, s[4:5]
	v_lshl_add_u64 v[14:15], v[14:15], 2, s[52:53]
	global_load_dword v12, v[14:15], off offset:-2048

; DI int TID() { int t = threadIdx.x; asm volatile("" : "+v"(t)); return t; }
; DI unsigned pk2(float a, float b) { f32x2_t v = {a, b}; bf16x2_t r_ = __builtin_convertvector(v, bf16x2_t); return __builtin_bit_cast(unsigned, r_); }
; template <bool MAP = false>
; DI void conv_tile(const float* __restrict__ src, int N, int K, bfu* __restrict__ dst, const float* __restrict__ g,
;                   int tk, int tn, char* smem, int ldk = -1) {
;   const int LK = ldk < 0 ? K : ldk;
;   float* T = (float*)smem;
;   const int tid = TID();
;   __syncthreads();
; #pragma unroll
;   for (int j = 0; j < 4; ++j) {
;     int k = (tid >> 4) + 16 * j, n4 = (tid & 15) * 4;
;     int gn = tn * 64 + n4, gk = tk * 64 + k;
;     float4 v = make_float4(0.f, 0.f, 0.f, 0.f);
;     const int og = MAP ? in_colmap(gn) : (gn < N ? gn : -1);
;     if (og >= 0) v = *(const float4*)(src + (size_t)gk * N + og);
;     float gg = g ? g[gk] : 1.f;
;     T[k * 65 + n4 + 0] = v.x * gg; T[k * 65 + n4 + 1] = v.y * gg; T[k * 65 + n4 + 2] = v.z * gg; T[k * 65 + n4 + 3] = v.w * gg;
;   }
;   __syncthreads();
; #pragma unroll
;   for (int j = 0; j < 2; ++j) {
;     int n = (tid >> 3) + 32 * j, kc = tid & 7;
;     float e[8];
; #pragma unroll
;     for (int q = 0; q < 8; ++q) e[q] = T[(kc * 8 + q) * 65 + n];
;     u32x4 o = {pk2(e[0], e[1]), pk2(e[2], e[3]), pk2(e[4], e[5]), pk2(e[6], e[7])};
;     *(u32x4*)(dst + (size_t)(tn * 64 + n) * LK + tk * 64 + kc * 8) = o;
;   }
; }
; DI void conv_item_C(const Params& p, int L, int it, char* smem) {
;     ...
;   else if (it < 512) { int t = it - 256; conv_tile(p.w_o + (size_t)L * D * D, D, D, p.wt_o, nullptr, t / 16, t % 16, smem); }
.LBB0_190:
	s_andn2_b64 vcc, exec, s[2:3]
	s_cbranch_vccnz .LBB0_192
	v_mov_b32_e32 v8, v224
	s_lshl_b32 s3, s6, 2
	s_lshl_b32 s2, s6, 6
	v_lshlrev_b32_e32 v0, 2, v8
	s_and_b32 s3, s3, 0x7c0
	v_ashrrev_i32_e32 v2, 4, v8
	v_and_b32_e32 v3, 60, v0
	s_and_b32 s2, s2, 0x3c0
	s_add_i32 s96, s3, 0xfffffc00
	v_or_b32_e32 v0, s2, v3
	v_readlane_b32 s4, v255, 28
	v_add_u32_e32 v6, s96, v2
	v_lshlrev_b32_e32 v188, 2, v0
	v_readlane_b32 s5, v255, 29
	v_ashrrev_i32_e32 v7, 31, v6
	v_lshlrev_b64 v[0:1], 12, v[6:7]
	v_lshl_add_u64 v[4:5], s[4:5], 0, v[188:189]
	s_movk_i32 s3, 0x104
	v_lshl_add_u64 v[0:1], v[4:5], 0, v[0:1]
	v_mul_lo_u32 v2, v2, s3
	s_waitcnt vmcnt(63) expcnt(7) lgkmcnt(15)
	s_barrier
	v_lshl_add_u32 v7, v3, 2, v2
	v_add_u32_e32 v210, 16, v6
	v_ashrrev_i32_e32 v211, 31, v210
	v_lshlrev_b64 v[210:211], 12, v[210:211]
	v_lshl_add_u64 v[210:211], v[4:5], 0, v[210:211]
	global_load_dwordx4 v[240:243], v[210:211], off
	v_add_u32_e32 v210, 32, v6
	v_ashrrev_i32_e32 v211, 31, v210
	v_lshlrev_b64 v[210:211], 12, v[210:211]
	v_lshl_add_u64 v[210:211], v[4:5], 0, v[210:211]
	global_load_dwordx4 v[244:247], v[210:211], off
	v_add_u32_e32 v210, 48, v6
	v_ashrrev_i32_e32 v211, 31, v210
	v_lshlrev_b64 v[210:211], 12, v[210:211]
	v_lshl_add_u64 v[210:211], v[4:5], 0, v[210:211]
	global_load_dwordx4 v[248:251], v[210:211], off
	global_load_dwordx4 v[0:3], v[0:1], off
	v_add_u32_e32 v9, 0x1040, v7
	v_ashrrev_i32_e32 v22, 3, v8
	v_readlane_b32 s16, v253, 48
	s_lshl_b64 s[4:5], s[96:97], 1
	v_readlane_b32 s22, v253, 54
	v_readlane_b32 s23, v253, 55
	s_add_u32 s4, s22, s4
	s_addc_u32 s5, s23, s5
	v_readlane_b32 s17, v253, 49
	v_readlane_b32 s18, v253, 50
	v_readlane_b32 s19, v253, 51
	v_readlane_b32 s20, v253, 52
	v_readlane_b32 s21, v253, 53
	v_readlane_b32 s24, v253, 56
	v_readlane_b32 s25, v253, 57
	v_readlane_b32 s26, v253, 58
	v_readlane_b32 s27, v253, 59
	v_readlane_b32 s28, v253, 60
	v_readlane_b32 s29, v253, 61
	v_readlane_b32 s30, v253, 62
	v_readlane_b32 s31, v253, 63
	s_waitcnt vmcnt(0)
	ds_write2_b32 v7, v0, v1 offset1:1
	ds_write2_b32 v7, v2, v3 offset0:2 offset1:3
	v_add_u32_e32 v0, 16, v6
	v_ashrrev_i32_e32 v1, 31, v0
	v_lshlrev_b64 v[0:1], 12, v[0:1]
	v_lshl_add_u64 v[0:1], v[4:5], 0, v[0:1]
	global_load_dwordx4 v[0:3], v[0:1], off
	s_waitcnt vmcnt(0)
	ds_write2_b32 v9, v0, v1 offset1:1
	v_add_u32_e32 v0, 0x1048, v7
	ds_write2_b32 v0, v2, v3 offset1:1
	v_add_u32_e32 v0, 32, v6
	v_ashrrev_i32_e32 v1, 31, v0
	v_lshlrev_b64 v[0:1], 12, v[0:1]
	v_lshl_add_u64 v[0:1], v[4:5], 0, v[0:1]
	global_load_dwordx4 v[0:3], v[0:1], off
	v_add_u32_e32 v9, 0x2080, v7
	s_waitcnt vmcnt(0)
	ds_write2_b32 v9, v0, v1 offset1:1
	v_add_u32_e32 v0, 0x2088, v7
	ds_write2_b32 v0, v2, v3 offset1:1
	v_add_u32_e32 v0, 48, v6
	v_ashrrev_i32_e32 v1, 31, v0
	v_lshlrev_b64 v[0:1], 12, v[0:1]
	v_lshl_add_u64 v[0:1], v[4:5], 0, v[0:1]
	global_load_dwordx4 v[0:3], v[0:1], off
	v_add_u32_e32 v4, 0x30c0, v7
	s_waitcnt vmcnt(0)
	ds_write2_b32 v4, v0, v1 offset1:1
	v_add_u32_e32 v0, 0x30c8, v7
	ds_write2_b32 v0, v2, v3 offset1:1
	v_lshlrev_b32_e32 v0, 3, v8
	v_and_b32_e32 v2, 56, v0
	v_lshlrev_b32_e32 v188, 1, v2
	v_mul_u32_u24_e32 v2, 0x104, v2
	v_lshl_add_u32 v2, v22, 2, v2
	s_waitcnt lgkmcnt(0)
	s_barrier
	ds_read2_b32 v[6:7], v2 offset1:32
	ds_read2_b32 v[8:9], v2 offset0:65 offset1:97
	ds_read2_b32 v[10:11], v2 offset0:130 offset1:162
	ds_read2_b32 v[12:13], v2 offset0:195 offset1:227
	v_add_u32_e32 v2, 0x400, v2
	ds_read2_b32 v[14:15], v2 offset0:4 offset1:36
	ds_read2_b32 v[16:17], v2 offset0:69 offset1:101
	ds_read2_b32 v[18:19], v2 offset0:134 offset1:166
	ds_read2_b32 v[20:21], v2 offset0:199 offset1:231
	v_add_u32_e32 v22, s2, v22
	v_ashrrev_i32_e32 v23, 31, v22
	v_lshl_add_u64 v[0:1], s[4:5], 0, v[188:189]
	v_lshlrev_b64 v[24:25], 11, v[22:23]
	s_waitcnt lgkmcnt(6)
	v_cvt_pk_bf16_f32 v2, v6, v8
	s_waitcnt lgkmcnt(4)
	v_cvt_pk_bf16_f32 v3, v10, v12
	s_waitcnt lgkmcnt(2)
	v_cvt_pk_bf16_f32 v4, v14, v16
	s_waitcnt lgkmcnt(0)
	v_cvt_pk_bf16_f32 v5, v18, v20
	v_lshl_add_u64 v[24:25], v[0:1], 0, v[24:25]
	v_add_u32_e32 v6, 32, v22
	global_store_dwordx4 v[24:25], v[2:5], off
	s_nop 1
	v_cvt_pk_bf16_f32 v2, v7, v9
	v_ashrrev_i32_e32 v7, 31, v6
	v_lshlrev_b64 v[6:7], 11, v[6:7]
	v_cvt_pk_bf16_f32 v3, v11, v13
	v_cvt_pk_bf16_f32 v4, v15, v17
	v_cvt_pk_bf16_f32 v5, v19, v21
	v_lshl_add_u64 v[0:1], v[0:1], 0, v[6:7]
	global_store_dwordx4 v[0:1], v[2:5], off

; DI int TID() { int t = threadIdx.x; asm volatile("" : "+v"(t)); return t; }
; DI unsigned pk2(float a, float b) { f32x2_t v = {a, b}; bf16x2_t r_ = __builtin_convertvector(v, bf16x2_t); return __builtin_bit_cast(unsigned, r_); }
; template <bool MAP = false>
; DI void conv_tile(const float* __restrict__ src, int N, int K, bfu* __restrict__ dst, const float* __restrict__ g,
;                   int tk, int tn, char* smem, int ldk = -1) {
;   const int LK = ldk < 0 ? K : ldk;
;   float* T = (float*)smem;
;   const int tid = TID();
;   __syncthreads();
; #pragma unroll
;   for (int j = 0; j < 4; ++j) {
;     int k = (tid >> 4) + 16 * j, n4 = (tid & 15) * 4;
;     int gn = tn * 64 + n4, gk = tk * 64 + k;
;     float4 v = make_float4(0.f, 0.f, 0.f, 0.f);
;     const int og = MAP ? in_colmap(gn) : (gn < N ? gn : -1);
;     if (og >= 0) v = *(const float4*)(src + (size_t)gk * N + og);
;     float gg = g ? g[gk] : 1.f;
;     T[k * 65 + n4 + 0] = v.x * gg; T[k * 65 + n4 + 1] = v.y * gg; T[k * 65 + n4 + 2] = v.z * gg; T[k * 65 + n4 + 3] = v.w * gg;
;   }
;   __syncthreads();
; #pragma unroll
;   for (int j = 0; j < 2; ++j) {
;     int n = (tid >> 3) + 32 * j, kc = tid & 7;
;     float e[8];
; #pragma unroll
;     for (int q = 0; q < 8; ++q) e[q] = T[(kc * 8 + q) * 65 + n];
;     u32x4 o = {pk2(e[0], e[1]), pk2(e[2], e[3]), pk2(e[4], e[5]), pk2(e[6], e[7])};
;     *(u32x4*)(dst + (size_t)(tn * 64 + n) * LK + tk * 64 + kc * 8) = o;
;   }
; }
; DI void conv_item_C(const Params& p, int L, int it, char* smem) {
;   if (it < 256) { int t = it; int n = t >> 6; t &= 63; conv_tile(p.w_branch + ((size_t)L * 4 + n) * 256 * D, D, 256, p.wt_br + (size_t)n * 256, nullptr, t / 16, t % 16, smem, 1024); }
.LBB0_193:
	s_andn2_b64 vcc, exec, s[2:3]
	s_cbranch_vccnz .LBB0_195
	s_lshr_b32 s96, s6, 6
	s_lshl_b64 s[2:3], s[96:97], 20
	s_add_u32 s4, s61, s2
	v_readlane_b32 s16, v253, 48
	s_addc_u32 s5, s89, s3
	s_lshl_b64 s[2:3], s[96:97], 9
	v_readlane_b32 s20, v253, 52
	v_readlane_b32 s21, v253, 53
	s_add_u32 s7, s20, s2
	v_mov_b32_e32 v8, v224
	s_addc_u32 s3, s21, s3
	s_lshl_b32 s2, s6, 6
	v_lshlrev_b32_e32 v0, 2, v8
	s_lshl_b32 s6, s6, 2
	v_ashrrev_i32_e32 v2, 4, v8
	v_and_b32_e32 v3, 60, v0
	s_and_b32 s2, s2, 0x3c0
	s_and_b32 s6, s6, 0xc0
	v_or_b32_e32 v0, s2, v3
	v_add_u32_e32 v6, s6, v2
	v_lshlrev_b32_e32 v188, 2, v0
	v_ashrrev_i32_e32 v7, 31, v6
	v_lshl_add_u64 v[4:5], s[4:5], 0, v[188:189]
	v_lshlrev_b64 v[0:1], 12, v[6:7]
	s_movk_i32 s4, 0x104
	v_lshl_add_u64 v[0:1], v[4:5], 0, v[0:1]
	v_mul_lo_u32 v2, v2, s4
	s_waitcnt vmcnt(63) expcnt(7) lgkmcnt(15)
	s_barrier
	v_lshl_add_u32 v7, v3, 2, v2
	v_add_u32_e32 v210, 16, v6
	v_ashrrev_i32_e32 v211, 31, v210
	v_lshlrev_b64 v[210:211], 12, v[210:211]
	v_lshl_add_u64 v[210:211], v[4:5], 0, v[210:211]
	global_load_dwordx4 v[240:243], v[210:211], off
	v_add_u32_e32 v210, 32, v6
	v_ashrrev_i32_e32 v211, 31, v210
	v_lshlrev_b64 v[210:211], 12, v[210:211]
	v_lshl_add_u64 v[210:211], v[4:5], 0, v[210:211]
	global_load_dwordx4 v[244:247], v[210:211], off
	v_add_u32_e32 v210, 48, v6
	v_ashrrev_i32_e32 v211, 31, v210
	v_lshlrev_b64 v[210:211], 12, v[210:211]
	v_lshl_add_u64 v[210:211], v[4:5], 0, v[210:211]
	global_load_dwordx4 v[248:251], v[210:211], off
	global_load_dwordx4 v[0:3], v[0:1], off
	v_add_u32_e32 v9, 0x1040, v7
	v_ashrrev_i32_e32 v22, 3, v8
	s_lshl_b32 s4, s6, 1
	s_add_u32 s4, s7, s4
	s_addc_u32 s5, s3, 0
	v_readlane_b32 s17, v253, 49
	v_readlane_b32 s18, v253, 50
	v_readlane_b32 s19, v253, 51
	v_readlane_b32 s22, v253, 54
	v_readlane_b32 s23, v253, 55
	v_readlane_b32 s24, v253, 56
	v_readlane_b32 s25, v253, 57
	v_readlane_b32 s26, v253, 58
	v_readlane_b32 s27, v253, 59
	v_readlane_b32 s28, v253, 60
	v_readlane_b32 s29, v253, 61
	v_readlane_b32 s30, v253, 62
	v_readlane_b32 s31, v253, 63
	s_waitcnt vmcnt(0)
	ds_write2_b32 v7, v0, v1 offset1:1
	ds_write2_b32 v7, v2, v3 offset0:2 offset1:3
	v_add_u32_e32 v0, 16, v6
	v_ashrrev_i32_e32 v1, 31, v0
	v_lshlrev_b64 v[0:1], 12, v[0:1]
	v_lshl_add_u64 v[0:1], v[4:5], 0, v[0:1]
	global_load_dwordx4 v[0:3], v[0:1], off
	s_waitcnt vmcnt(0)
	ds_write2_b32 v9, v0, v1 offset1:1
	v_add_u32_e32 v0, 0x1048, v7
	ds_write2_b32 v0, v2, v3 offset1:1
	v_add_u32_e32 v0, 32, v6
	v_ashrrev_i32_e32 v1, 31, v0
	v_lshlrev_b64 v[0:1], 12, v[0:1]
	v_lshl_add_u64 v[0:1], v[4:5], 0, v[0:1]
	global_load_dwordx4 v[0:3], v[0:1], off
	v_add_u32_e32 v9, 0x2080, v7
	s_waitcnt vmcnt(0)
	ds_write2_b32 v9, v0, v1 offset1:1
	v_add_u32_e32 v0, 0x2088, v7
	ds_write2_b32 v0, v2, v3 offset1:1
	v_add_u32_e32 v0, 48, v6
	v_ashrrev_i32_e32 v1, 31, v0
	v_lshlrev_b64 v[0:1], 12, v[0:1]
	v_lshl_add_u64 v[0:1], v[4:5], 0, v[0:1]
	global_load_dwordx4 v[0:3], v[0:1], off
	v_add_u32_e32 v4, 0x30c0, v7
	s_waitcnt vmcnt(0)
	ds_write2_b32 v4, v0, v1 offset1:1
	v_add_u32_e32 v0, 0x30c8, v7
	ds_write2_b32 v0, v2, v3 offset1:1
	v_lshlrev_b32_e32 v0, 3, v8
	v_and_b32_e32 v2, 56, v0
	v_lshlrev_b32_e32 v188, 1, v2
	v_mul_u32_u24_e32 v2, 0x104, v2
	v_lshl_add_u32 v2, v22, 2, v2
	s_waitcnt lgkmcnt(0)
	s_barrier
	ds_read2_b32 v[6:7], v2 offset1:32
	ds_read2_b32 v[8:9], v2 offset0:65 offset1:97
	ds_read2_b32 v[10:11], v2 offset0:130 offset1:162
	ds_read2_b32 v[12:13], v2 offset0:195 offset1:227
	v_add_u32_e32 v2, 0x400, v2
	ds_read2_b32 v[14:15], v2 offset0:4 offset1:36
	ds_read2_b32 v[16:17], v2 offset0:69 offset1:101
	ds_read2_b32 v[18:19], v2 offset0:134 offset1:166
	ds_read2_b32 v[20:21], v2 offset0:199 offset1:231
	v_add_u32_e32 v22, s2, v22
	v_ashrrev_i32_e32 v23, 31, v22
	v_lshl_add_u64 v[0:1], s[4:5], 0, v[188:189]
	v_lshlrev_b64 v[24:25], 11, v[22:23]
	s_waitcnt lgkmcnt(6)
	v_cvt_pk_bf16_f32 v2, v6, v8
	s_waitcnt lgkmcnt(4)
	v_cvt_pk_bf16_f32 v3, v10, v12
	s_waitcnt lgkmcnt(2)
	v_cvt_pk_bf16_f32 v4, v14, v16
	s_waitcnt lgkmcnt(0)
	v_cvt_pk_bf16_f32 v5, v18, v20
	v_lshl_add_u64 v[24:25], v[0:1], 0, v[24:25]
	v_add_u32_e32 v6, 32, v22
	global_store_dwordx4 v[24:25], v[2:5], off
	s_nop 1
	v_cvt_pk_bf16_f32 v2, v7, v9
	v_ashrrev_i32_e32 v7, 31, v6
	v_lshlrev_b64 v[6:7], 11, v[6:7]
	v_cvt_pk_bf16_f32 v3, v11, v13
	v_cvt_pk_bf16_f32 v4, v15, v17
	v_cvt_pk_bf16_f32 v5, v19, v21
	v_lshl_add_u64 v[0:1], v[0:1], 0, v[6:7]
	global_store_dwordx4 v[0:1], v[2:5], off

; DI int TID() { int t = threadIdx.x; asm volatile("" : "+v"(t)); return t; }
; template <int MODE>
; DI void attn_run(const bfu* __restrict__ Qp, const bfu* __restrict__ Kp, const bfu* __restrict__ Vtp, int qt,
;                  f32x16 (&o)[2], const float* __restrict__ cump, unsigned sel, unsigned blockmask, char* smem) {
;     ...
;   const int tid = TID(), lane = tid & 63, w = tid >> 6, r = lane & 31, hh = lane >> 5;
;   const int q0 = qt * 128;
;   const int t = q0 + w * 32 + r;
;   const int tw_min = q0 + w * 32, tw_max = tw_min + 31;
;   bf16x8 qf[NKS];
; #pragma unroll
;   for (int ks = 0; ks < NKS; ++ks) qf[ks] = *(const bf16x8*)(Qp + (size_t)t * DK + ks * 16 + hh * 8);
;   float cumq = 0.f;
;   if (MODE == 2) cumq = cump[t];
;   bf16x8 U[2];
;   if (MODE == 0) {
; #pragma unroll
;     for (int s2 = 0; s2 < 2; ++s2)
; #pragma unroll
;       for (int j = 0; j < 8; ++j) { int kk = 16 * s2 + 8 * (j >> 2) + 4 * hh + (j & 3); U[s2][j] = (kk > r) ? (short)0x3F80 : (short)0; }
;   }
; #pragma unroll
;   for (int dt = 0; dt < 2; ++dt)
; #pragma unroll
;     for (int i = 0; i < 16; ++i) o[dt][i] = 0.f;
;   float m = -INFINITY, l = 0.f, carry = 0.f;
;   int kt_lo = 0, kt_hi = 2 * qt + 1;
;   if (MODE == 4) kt_lo = (2 * qt - 8) > 0 ? (2 * qt - 8) : 0;
;   int kt;
;   if (MODE == 0) kt = kt_hi;
;   else if (MODE == 3) { kt = kt_lo; while (kt <= kt_hi && !((blockmask >> kt) & 1u)) ++kt; }
;   else kt = kt_lo;
;   u32x4 rk[NKC], rv[2]; float rc = 0.f;
;     ...
;   if (kt <= kt_hi && kt >= 0) { ATT_LOAD(kt) }
; DI void phase_attn2(const Params& p, char* smem) {
;   for (int it = blockIdx.x; it < 1024; it += gridDim.x) {
;     const int j = (it & 511) >> 1;
;     const int idx = (it < 512) ? j : (511 - j);
;     if (it & 1) attn_item<1>(p, idx, smem); else attn_item<3>(p, idx, smem);
.LBB0_409:
	s_bfe_u32 s2, s93, 0x80001
	s_xor_b32 s3, s2, 0x1ff
	s_cmpk_lt_i32 s93, 0x200
	s_cselect_b32 s7, s2, s3
	s_lshr_b32 s3, s93, 9
	s_xor_b32 s3, s3, s93
	s_bitcmp0_b32 s3, 0
	s_mov_b64 s[2:3], -1
	s_cbranch_scc1 .LBB0_433
	v_mov_b32_e32 v118, v224
	s_waitcnt vmcnt(63) expcnt(7) lgkmcnt(15)
	v_cmp_gt_i32_e32 vcc, 4, v118
	s_barrier
	s_and_saveexec_b64 s[2:3], vcc
	v_lshlrev_b32_e32 v0, 2, v118
	ds_write_b32 v0, v189 offset:22784
	s_or_b64 exec, exec, s[2:3]
	s_not_b32 s2, s7
	s_lshl_b32 s2, s2, 2
	s_and_b32 s8, s7, 31
	v_readlane_b32 s16, v254, 20
	v_mov_b32_e32 v10, v224
	s_and_b32 s6, s2, 0x780
	s_mul_i32 s2, s8, 0x60000
	v_readlane_b32 s22, v254, 26
	v_readlane_b32 s23, v254, 27
	v_ashrrev_i32_e32 v0, 1, v10
	s_add_u32 s4, s22, s2
	v_and_b32_e32 v0, 0xffffffe0, v0
	s_addc_u32 s5, s23, 0
	v_and_b32_e32 v18, 31, v10
	v_add_u32_e32 v124, s6, v0
	v_bfe_u32 v19, v10, 5, 1
	v_or_b32_e32 v122, v124, v18
	v_mov_b64_e32 v[0:1], s[4:5]
	s_movk_i32 s11, 0xc0
	v_mad_i64_i32 v[0:1], s[4:5], v122, s11, v[0:1]
	v_lshlrev_b32_e32 v188, 4, v19
	v_lshl_add_u64 v[0:1], v[0:1], 0, v[188:189]
	s_mov_b32 s10, 0x2aaaaaab
	global_load_dwordx4 v[64:67], v[0:1], off
	global_load_dwordx4 v[112:115], v[0:1], off offset:32
	global_load_dwordx4 v[108:111], v[0:1], off offset:64
	global_load_dwordx4 v[104:107], v[0:1], off offset:96
	global_load_dwordx4 v[100:103], v[0:1], off offset:128
	global_load_dwordx4 v[96:99], v[0:1], off offset:160
	v_mul_hi_i32 v0, v10, s10
	v_add_u32_e32 v14, 0x100, v10
	v_lshrrev_b32_e32 v1, 31, v0
	v_ashrrev_i32_e32 v0, 1, v0
	v_mul_hi_i32 v6, v14, s10
	v_readlane_b32 s17, v254, 21
	v_readlane_b32 s18, v254, 22
	v_readlane_b32 s19, v254, 23
	v_add_u32_e32 v20, v0, v1
	v_lshrrev_b32_e32 v7, 31, v6
	v_ashrrev_i32_e32 v6, 1, v6
	v_readlane_b32 s16, v255, 14
	v_mul_lo_u32 v0, v20, 12
	v_add_u32_e32 v22, v6, v7
	v_readlane_b32 s17, v255, 15
	s_add_u32 s2, s16, s2
	v_sub_u32_e32 v21, v10, v0
	v_mul_lo_u32 v6, v22, 12
	s_addc_u32 s3, s17, 0
	v_lshlrev_b32_e32 v4, 3, v21
	v_sub_u32_e32 v23, v14, v6
	v_mov_b64_e32 v[0:1], s[2:3]
	v_ashrrev_i32_e32 v5, 31, v4
	v_lshlrev_b32_e32 v8, 3, v23
	v_mad_i64_i32 v[2:3], s[4:5], v20, s11, v[0:1]
	v_lshlrev_b64 v[4:5], 1, v[4:5]
	v_ashrrev_i32_e32 v9, 31, v8
	v_lshl_add_u64 v[2:3], v[2:3], 0, v[4:5]
	v_mad_i64_i32 v[6:7], s[4:5], v22, s11, v[0:1]
	v_lshlrev_b64 v[8:9], 1, v[8:9]
	v_lshl_add_u64 v[6:7], v[6:7], 0, v[8:9]
	global_load_dwordx4 v[72:75], v[2:3], off
	global_load_dwordx4 v[68:71], v[6:7], off
	v_add_u32_e32 v2, 0x200, v10
	v_mul_hi_i32 v3, v2, s10
	v_lshrrev_b32_e32 v6, 31, v3
	v_ashrrev_i32_e32 v3, 1, v3
	v_add_u32_e32 v24, v3, v6
	v_mul_lo_u32 v3, v24, 12
	v_sub_u32_e32 v25, v2, v3
	v_lshlrev_b32_e32 v2, 3, v25
	v_ashrrev_i32_e32 v3, 31, v2
	v_mad_i64_i32 v[0:1], s[4:5], v24, s11, v[0:1]
	v_lshlrev_b64 v[2:3], 1, v[2:3]
	v_readlane_b32 s18, v255, 16
	s_lshl_b32 s96, s8, 18
	v_lshl_add_u64 v[0:1], v[0:1], 0, v[2:3]
	v_readlane_b32 s19, v255, 17
	s_add_u32 s8, s18, s96
	global_load_dwordx4 v[76:79], v[0:1], off
	v_lshlrev_b32_e32 v0, 4, v10
	v_ashrrev_i32_e32 v6, 3, v10
	s_addc_u32 s9, s19, 0
	v_and_b32_e32 v32, 0x70, v0
	v_mov_b32_e32 v33, v189
	v_ashrrev_i32_e32 v7, 31, v6
	v_ashrrev_i32_e32 v14, 3, v14
	v_lshl_add_u64 v[0:1], s[8:9], 0, v[32:33]
	v_lshlrev_b64 v[10:11], 12, v[6:7]
	v_ashrrev_i32_e32 v15, 31, v14
	v_lshl_add_u64 v[12:13], v[0:1], 0, v[10:11]
	v_lshlrev_b64 v[16:17], 12, v[14:15]
	v_lshl_add_u64 v[0:1], v[0:1], 0, v[16:17]
	global_load_dwordx4 v[84:87], v[12:13], off
	global_load_dwordx4 v[80:83], v[0:1], off
	s_movk_i32 s4, 0xd0
	v_lshlrev_b32_e32 v0, 3, v19
	v_mul_lo_u32 v33, v20, s4
	v_mul_lo_u32 v35, v22, s4
	v_mul_lo_u32 v37, v24, s4
	s_movk_i32 s4, 0x88
	v_sub_u32_e32 v120, v188, v0
	v_mul_lo_u32 v39, v6, s4
	v_mul_lo_u32 v40, v14, s4
	v_lshl_add_u64 v[0:1], s[96:97], 0, v[10:11]
	v_readlane_b32 s4, v255, 18
	v_or_b32_e32 v0, v0, v32
	v_readlane_b32 s5, v255, 19
	s_mov_b64 s[8:9], 0x3000
	v_lshlrev_b32_e32 v34, 4, v21
	s_waitcnt vmcnt(12)
	v_lshl_add_u64 v[88:89], s[4:5], 0, v[0:1]
	v_lshl_add_u64 v[0:1], s[96:97], 0, v[16:17]
	v_or_b32_e32 v0, v0, v32
	v_lshl_add_u64 v[90:91], s[4:5], 0, v[0:1]
	v_mad_i64_i32 v[0:1], s[4:5], v24, s11, v[2:3]
	s_waitcnt vmcnt(11)
	v_lshl_add_u64 v[92:93], v[0:1], 0, s[8:9]
	v_mad_i64_i32 v[0:1], s[4:5], v22, s11, v[8:9]
	v_lshl_add_u64 v[94:95], v[0:1], 0, s[8:9]
	v_mad_i64_i32 v[0:1], s[4:5], v20, s11, v[4:5]
	v_lshlrev_b32_e32 v36, 4, v23
	v_lshlrev_b32_e32 v38, 4, v25
	s_movk_i32 s4, 0x3400
	v_or_b32_e32 v126, 31, v124
	v_lshlrev_b32_e32 v123, 2, v19
	v_mul_u32_u24_e32 v125, 0xd0, v18
	v_mul_u32_u24_e32 v121, 0x88, v18
	s_or_b32 s10, s6, 64
	v_lshl_add_u64 v[116:117], v[0:1], 0, s[8:9]
	s_mov_b32 s11, 0
	v_mov_b32_e32 v0, v189
	v_mov_b32_e32 v1, v189
	v_mov_b32_e32 v2, v189
	v_mov_b32_e32 v3, v189
	v_mov_b32_e32 v4, v189
	v_mov_b32_e32 v5, v189
	v_mov_b32_e32 v6, v189
	v_mov_b32_e32 v7, v189
	v_mov_b32_e32 v8, v189
	v_mov_b32_e32 v9, v189
	v_mov_b32_e32 v10, v189
	v_mov_b32_e32 v11, v189
	v_mov_b32_e32 v12, v189
	v_mov_b32_e32 v13, v189
	v_mov_b32_e32 v14, v189
	v_mov_b32_e32 v15, v189
	v_mov_b32_e32 v16, v189
	v_mov_b32_e32 v17, v189
	v_mov_b32_e32 v18, v189
	v_mov_b32_e32 v19, v189
	v_mov_b32_e32 v20, v189
	v_mov_b32_e32 v21, v189
	v_mov_b32_e32 v22, v189
	v_mov_b32_e32 v23, v189
	v_mov_b32_e32 v24, v189
	v_mov_b32_e32 v25, v189
	v_mov_b32_e32 v26, v189
	v_mov_b32_e32 v27, v189
	v_mov_b32_e32 v28, v189
	v_mov_b32_e32 v29, v189
	v_mov_b32_e32 v30, v189
	v_mov_b32_e32 v31, v189
	v_mov_b32_e32 v132, 0xff800000
	v_mov_b32_e32 v119, 0
	v_add_u32_e32 v127, v33, v34
	v_add_u32_e32 v128, v35, v36
	v_add_u32_e32 v129, v37, v38
	v_add3_u32 v130, v32, v39, s4
	v_add3_u32 v131, v32, v40, s4
	v_readlane_b32 s20, v254, 24
	v_readlane_b32 s21, v254, 25
	s_branch .LBB0_415

; DI int TID() { int t = threadIdx.x; asm volatile("" : "+v"(t)); return t; }
; DI unsigned pk2(float a, float b) { f32x2_t v = {a, b}; bf16x2_t r_ = __builtin_convertvector(v, bf16x2_t); return __builtin_bit_cast(unsigned, r_); }
; template <bool MAP = false>
; DI void conv_tile(const float* __restrict__ src, int N, int K, bfu* __restrict__ dst, const float* __restrict__ g,
;                   int tk, int tn, char* smem, int ldk = -1) {
;   const int LK = ldk < 0 ? K : ldk;
;   float* T = (float*)smem;
;   const int tid = TID();
;   __syncthreads();
; #pragma unroll
;   for (int j = 0; j < 4; ++j) {
;     int k = (tid >> 4) + 16 * j, n4 = (tid & 15) * 4;
;     int gn = tn * 64 + n4, gk = tk * 64 + k;
;     float4 v = make_float4(0.f, 0.f, 0.f, 0.f);
;     const int og = MAP ? in_colmap(gn) : (gn < N ? gn : -1);
;     if (og >= 0) v = *(const float4*)(src + (size_t)gk * N + og);
;     float gg = g ? g[gk] : 1.f;
;     T[k * 65 + n4 + 0] = v.x * gg; T[k * 65 + n4 + 1] = v.y * gg; T[k * 65 + n4 + 2] = v.z * gg; T[k * 65 + n4 + 3] = v.w * gg;
;   }
;   __syncthreads();
; #pragma unroll
;   for (int j = 0; j < 2; ++j) {
;     int n = (tid >> 3) + 32 * j, kc = tid & 7;
;     float e[8];
; #pragma unroll
;     for (int q = 0; q < 8; ++q) e[q] = T[(kc * 8 + q) * 65 + n];
;     u32x4 o = {pk2(e[0], e[1]), pk2(e[2], e[3]), pk2(e[4], e[5]), pk2(e[6], e[7])};
;     *(u32x4*)(dst + (size_t)(tn * 64 + n) * LK + tk * 64 + kc * 8) = o;
;   }
; }
; DI void conv_item_C(const Params& p, int L, int it, char* smem) {
;     ...
;   else if (it < 2880) { int t = it - 2816; conv_tile(p.w_ple_proj + (size_t)L * 256 * D, D, 256, p.wt_pp, nullptr, t / 16, t % 16, smem); }
.LBB0_1918:
	s_andn2_b64 vcc, exec, s[2:3]
	s_cbranch_vccnz .LBB0_1920
	v_mov_b32_e32 v8, v224
	s_lshl_b32 s3, s12, 2
	s_lshl_b32 s2, s12, 6
	v_lshlrev_b32_e32 v0, 2, v8
	s_and_b32 s3, s3, 0x3fc0
	v_ashrrev_i32_e32 v2, 4, v8
	v_and_b32_e32 v3, 60, v0
	s_and_b32 s2, s2, 0x3c0
	s_add_i32 s96, s3, 0xffffd400
	v_or_b32_e32 v0, s2, v3
	v_add_u32_e32 v6, s96, v2
	v_lshlrev_b32_e32 v188, 2, v0
	v_ashrrev_i32_e32 v7, 31, v6
	v_lshl_add_u64 v[4:5], s[62:63], 0, v[188:189]
	v_lshlrev_b64 v[0:1], 12, v[6:7]
	s_movk_i32 s3, 0x104
	v_lshl_add_u64 v[0:1], v[4:5], 0, v[0:1]
	v_mul_lo_u32 v2, v2, s3
	s_waitcnt vmcnt(63) expcnt(7) lgkmcnt(15)
	s_barrier
	v_lshl_add_u32 v7, v3, 2, v2
	v_add_u32_e32 v210, 16, v6
	v_ashrrev_i32_e32 v211, 31, v210
	v_lshlrev_b64 v[210:211], 12, v[210:211]
	v_lshl_add_u64 v[210:211], v[4:5], 0, v[210:211]
	global_load_dwordx4 v[240:243], v[210:211], off
	v_add_u32_e32 v210, 32, v6
	v_ashrrev_i32_e32 v211, 31, v210
	v_lshlrev_b64 v[210:211], 12, v[210:211]
	v_lshl_add_u64 v[210:211], v[4:5], 0, v[210:211]
	global_load_dwordx4 v[244:247], v[210:211], off
	v_add_u32_e32 v210, 48, v6
	v_ashrrev_i32_e32 v211, 31, v210
	v_lshlrev_b64 v[210:211], 12, v[210:211]
	v_lshl_add_u64 v[210:211], v[4:5], 0, v[210:211]
	global_load_dwordx4 v[248:251], v[210:211], off
	global_load_dwordx4 v[0:3], v[0:1], off
	v_add_u32_e32 v9, 0x1040, v7
	v_ashrrev_i32_e32 v22, 3, v8
	v_readlane_b32 s16, v253, 48
	s_lshl_b64 s[4:5], s[96:97], 1
	v_readlane_b32 s30, v253, 62
	v_readlane_b32 s31, v253, 63
	s_add_u32 s4, s30, s4
	s_addc_u32 s5, s31, s5
	v_readlane_b32 s17, v253, 49
	v_readlane_b32 s18, v253, 50
	v_readlane_b32 s19, v253, 51
	v_readlane_b32 s20, v253, 52
	v_readlane_b32 s21, v253, 53
	v_readlane_b32 s22, v253, 54
	v_readlane_b32 s23, v253, 55
	v_readlane_b32 s24, v253, 56
	v_readlane_b32 s25, v253, 57
	v_readlane_b32 s26, v253, 58
	v_readlane_b32 s27, v253, 59
	v_readlane_b32 s28, v253, 60
	v_readlane_b32 s29, v253, 61
	s_waitcnt vmcnt(0)
	ds_write2_b32 v7, v0, v1 offset1:1
	ds_write2_b32 v7, v2, v3 offset0:2 offset1:3
	v_add_u32_e32 v0, 16, v6
	v_ashrrev_i32_e32 v1, 31, v0
	v_lshlrev_b64 v[0:1], 12, v[0:1]
	v_lshl_add_u64 v[0:1], v[4:5], 0, v[0:1]
	global_load_dwordx4 v[0:3], v[0:1], off
	s_waitcnt vmcnt(0)
	ds_write2_b32 v9, v0, v1 offset1:1
	v_add_u32_e32 v0, 0x1048, v7
	ds_write2_b32 v0, v2, v3 offset1:1
	v_add_u32_e32 v0, 32, v6
	v_ashrrev_i32_e32 v1, 31, v0
	v_lshlrev_b64 v[0:1], 12, v[0:1]
	v_lshl_add_u64 v[0:1], v[4:5], 0, v[0:1]
	global_load_dwordx4 v[0:3], v[0:1], off
	v_add_u32_e32 v9, 0x2080, v7
	s_waitcnt vmcnt(0)
	ds_write2_b32 v9, v0, v1 offset1:1
	v_add_u32_e32 v0, 0x2088, v7
	ds_write2_b32 v0, v2, v3 offset1:1
	v_add_u32_e32 v0, 48, v6
	v_ashrrev_i32_e32 v1, 31, v0
	v_lshlrev_b64 v[0:1], 12, v[0:1]
	v_lshl_add_u64 v[0:1], v[4:5], 0, v[0:1]
	global_load_dwordx4 v[0:3], v[0:1], off
	v_add_u32_e32 v4, 0x30c0, v7
	s_waitcnt vmcnt(0)
	ds_write2_b32 v4, v0, v1 offset1:1
	v_add_u32_e32 v0, 0x30c8, v7
	ds_write2_b32 v0, v2, v3 offset1:1
	v_lshlrev_b32_e32 v0, 3, v8
	v_and_b32_e32 v2, 56, v0
	v_lshlrev_b32_e32 v188, 1, v2
	v_mul_u32_u24_e32 v2, 0x104, v2
	v_lshl_add_u32 v2, v22, 2, v2
	s_waitcnt lgkmcnt(0)
	s_barrier
	ds_read2_b32 v[6:7], v2 offset1:32
	ds_read2_b32 v[8:9], v2 offset0:65 offset1:97
	ds_read2_b32 v[10:11], v2 offset0:130 offset1:162
	ds_read2_b32 v[12:13], v2 offset0:195 offset1:227
	v_add_u32_e32 v2, 0x400, v2
	ds_read2_b32 v[14:15], v2 offset0:4 offset1:36
	ds_read2_b32 v[16:17], v2 offset0:69 offset1:101
	ds_read2_b32 v[18:19], v2 offset0:134 offset1:166
	ds_read2_b32 v[20:21], v2 offset0:199 offset1:231
	v_add_u32_e32 v22, s2, v22
	v_ashrrev_i32_e32 v23, 31, v22
	v_lshl_add_u64 v[0:1], s[4:5], 0, v[188:189]
	v_lshlrev_b64 v[24:25], 9, v[22:23]
	s_waitcnt lgkmcnt(6)
	v_cvt_pk_bf16_f32 v2, v6, v8
	s_waitcnt lgkmcnt(4)
	v_cvt_pk_bf16_f32 v3, v10, v12
	s_waitcnt lgkmcnt(2)
	v_cvt_pk_bf16_f32 v4, v14, v16
	s_waitcnt lgkmcnt(0)
	v_cvt_pk_bf16_f32 v5, v18, v20
	v_lshl_add_u64 v[24:25], v[0:1], 0, v[24:25]
	v_add_u32_e32 v6, 32, v22
	global_store_dwordx4 v[24:25], v[2:5], off
	s_nop 1
	v_cvt_pk_bf16_f32 v2, v7, v9
	v_ashrrev_i32_e32 v7, 31, v6
	v_lshlrev_b64 v[6:7], 9, v[6:7]
	v_cvt_pk_bf16_f32 v3, v11, v13
	v_cvt_pk_bf16_f32 v4, v15, v17
	v_cvt_pk_bf16_f32 v5, v19, v21
	v_lshl_add_u64 v[0:1], v[0:1], 0, v[6:7]
	global_store_dwordx4 v[0:1], v[2:5], off

; DI int TID() { int t = threadIdx.x; asm volatile("" : "+v"(t)); return t; }
; template <bool MAP = false>
; DI void conv_tile(const float* __restrict__ src, int N, int K, bfu* __restrict__ dst, const float* __restrict__ g,
;                   int tk, int tn, char* smem, int ldk = -1) {
;   const int LK = ldk < 0 ? K : ldk;
;   float* T = (float*)smem;
;   const int tid = TID();
;   __syncthreads();
; #pragma unroll
;   for (int j = 0; j < 4; ++j) {
;     int k = (tid >> 4) + 16 * j, n4 = (tid & 15) * 4;
;     int gn = tn * 64 + n4, gk = tk * 64 + k;
;     float4 v = make_float4(0.f, 0.f, 0.f, 0.f);
;     const int og = MAP ? in_colmap(gn) : (gn < N ? gn : -1);
;     if (og >= 0) v = *(const float4*)(src + (size_t)gk * N + og);
;     float gg = g ? g[gk] : 1.f;
;     T[k * 65 + n4 + 0] = v.x * gg; T[k * 65 + n4 + 1] = v.y * gg; T[k * 65 + n4 + 2] = v.z * gg; T[k * 65 + n4 + 3] = v.w * gg;
;   }
;   __syncthreads();
; DI void conv_item_C(const Params& p, int L, int it, char* smem) {
;     ...
;   else if (it < 2816) { int t = it - 2560; conv_tile(p.w_ple_gate + (size_t)L * D * D, D, D, p.wt_pg, p.norm_ple_g + L * D, t / 16, t % 16, smem); }
.LBB0_1921:
	s_andn2_b64 vcc, exec, s[2:3]
	s_cbranch_vccnz .LBB0_1931
	s_lshl_b32 s2, s12, 6
	v_mov_b32_e32 v11, v224
	s_and_b32 s4, s2, 0x3c0
	s_lshl_b32 s2, s12, 2
	s_and_b32 s2, s2, 0x3fc0
	v_lshlrev_b32_e32 v0, 2, v11
	v_ashrrev_i32_e32 v13, 4, v11
	v_and_b32_e32 v14, 60, v0
	s_add_i32 s96, s2, 0xffffd800
	v_or_b32_e32 v0, s4, v14
	v_add_u32_e32 v8, s96, v13
	v_lshlrev_b32_e32 v188, 2, v0
	v_ashrrev_i32_e32 v9, 31, v8
	v_lshl_add_u64 v[6:7], s[64:65], 0, v[188:189]
	v_lshlrev_b64 v[0:1], 12, v[8:9]
	v_lshl_add_u64 v[0:1], v[6:7], 0, v[0:1]
	s_waitcnt vmcnt(63) expcnt(7) lgkmcnt(15)
	s_barrier
	v_add_u32_e32 v210, 16, v8
	v_ashrrev_i32_e32 v211, 31, v210
	v_lshlrev_b64 v[210:211], 12, v[210:211]
	v_lshl_add_u64 v[210:211], v[6:7], 0, v[210:211]
	global_load_dwordx4 v[240:243], v[210:211], off
	v_add_u32_e32 v210, 32, v8
	v_ashrrev_i32_e32 v211, 31, v210
	v_lshlrev_b64 v[210:211], 12, v[210:211]
	v_lshl_add_u64 v[210:211], v[6:7], 0, v[210:211]
	global_load_dwordx4 v[244:247], v[210:211], off
	v_add_u32_e32 v210, 48, v8
	v_ashrrev_i32_e32 v211, 31, v210
	v_lshlrev_b64 v[210:211], 12, v[210:211]
	v_lshl_add_u64 v[210:211], v[6:7], 0, v[210:211]
	global_load_dwordx4 v[248:251], v[210:211], off
	global_load_dwordx4 v[0:3], v[0:1], off
	v_readlane_b32 s16, v255, 4
	v_readlane_b32 s17, v255, 5
	v_mov_b32_e32 v10, 1.0
	s_andn2_b64 vcc, exec, s[16:17]
	v_cndmask_b32_e64 v4, 0, 1, s[16:17]
	v_cmp_ne_u32_e64 s[2:3], 1, v4
	v_lshl_add_u64 v[4:5], v[8:9], 2, s[66:67]
	v_mov_b32_e32 v12, 1.0
	s_cbranch_vccnz .LBB0_1924
	global_load_dword v12, v[4:5], off

; DI int TID() { int t = threadIdx.x; asm volatile("" : "+v"(t)); return t; }
; DI unsigned pk2(float a, float b) { f32x2_t v = {a, b}; bf16x2_t r_ = __builtin_convertvector(v, bf16x2_t); return __builtin_bit_cast(unsigned, r_); }
; template <bool MAP = false>
; DI void conv_tile(const float* __restrict__ src, int N, int K, bfu* __restrict__ dst, const float* __restrict__ g,
;                   int tk, int tn, char* smem, int ldk = -1) {
;   const int LK = ldk < 0 ? K : ldk;
;   float* T = (float*)smem;
;   const int tid = TID();
;   __syncthreads();
; #pragma unroll
;   for (int j = 0; j < 4; ++j) {
;     int k = (tid >> 4) + 16 * j, n4 = (tid & 15) * 4;
;     int gn = tn * 64 + n4, gk = tk * 64 + k;
;     float4 v = make_float4(0.f, 0.f, 0.f, 0.f);
;     const int og = MAP ? in_colmap(gn) : (gn < N ? gn : -1);
;     if (og >= 0) v = *(const float4*)(src + (size_t)gk * N + og);
;     float gg = g ? g[gk] : 1.f;
;     T[k * 65 + n4 + 0] = v.x * gg; T[k * 65 + n4 + 1] = v.y * gg; T[k * 65 + n4 + 2] = v.z * gg; T[k * 65 + n4 + 3] = v.w * gg;
;   }
;   __syncthreads();
; #pragma unroll
;   for (int j = 0; j < 2; ++j) {
;     int n = (tid >> 3) + 32 * j, kc = tid & 7;
;     float e[8];
; #pragma unroll
;     for (int q = 0; q < 8; ++q) e[q] = T[(kc * 8 + q) * 65 + n];
;     u32x4 o = {pk2(e[0], e[1]), pk2(e[2], e[3]), pk2(e[4], e[5]), pk2(e[6], e[7])};
;     *(u32x4*)(dst + (size_t)(tn * 64 + n) * LK + tk * 64 + kc * 8) = o;
;   }
; }
; DI void conv_item_C(const Params& p, int L, int it, char* smem) {
;     ...
;   else if (it < 2560) { int t = it - 1536; conv_tile(p.w_down + (size_t)L * DFF * D, D, DFF, p.wt_down, nullptr, t / 16, t % 16, smem); }
.LBB0_1932:
	s_andn2_b64 vcc, exec, s[2:3]
	s_cbranch_vccnz .LBB0_1934
	v_mov_b32_e32 v8, v224
	s_lshl_b32 s3, s12, 2
	s_lshl_b32 s2, s12, 6
	v_lshlrev_b32_e32 v0, 2, v8
	s_and_b32 s3, s3, 0x3fc0
	v_ashrrev_i32_e32 v2, 4, v8
	v_and_b32_e32 v3, 60, v0
	s_and_b32 s2, s2, 0x3c0
	s_add_i32 s96, s3, 0xffffe800
	v_or_b32_e32 v0, s2, v3
	v_add_u32_e32 v6, s96, v2
	v_lshlrev_b32_e32 v188, 2, v0
	v_ashrrev_i32_e32 v7, 31, v6
	v_lshl_add_u64 v[4:5], s[92:93], 0, v[188:189]
	v_lshlrev_b64 v[0:1], 12, v[6:7]
	s_movk_i32 s3, 0x104
	v_lshl_add_u64 v[0:1], v[4:5], 0, v[0:1]
	v_mul_lo_u32 v2, v2, s3
	s_waitcnt vmcnt(63) expcnt(7) lgkmcnt(15)
	s_barrier
	v_lshl_add_u32 v7, v3, 2, v2
	v_add_u32_e32 v210, 16, v6
	v_ashrrev_i32_e32 v211, 31, v210
	v_lshlrev_b64 v[210:211], 12, v[210:211]
	v_lshl_add_u64 v[210:211], v[4:5], 0, v[210:211]
	global_load_dwordx4 v[240:243], v[210:211], off
	v_add_u32_e32 v210, 32, v6
	v_ashrrev_i32_e32 v211, 31, v210
	v_lshlrev_b64 v[210:211], 12, v[210:211]
	v_lshl_add_u64 v[210:211], v[4:5], 0, v[210:211]
	global_load_dwordx4 v[244:247], v[210:211], off
	v_add_u32_e32 v210, 48, v6
	v_ashrrev_i32_e32 v211, 31, v210
	v_lshlrev_b64 v[210:211], 12, v[210:211]
	v_lshl_add_u64 v[210:211], v[4:5], 0, v[210:211]
	global_load_dwordx4 v[248:251], v[210:211], off
	global_load_dwordx4 v[0:3], v[0:1], off
	v_add_u32_e32 v9, 0x1040, v7
	v_ashrrev_i32_e32 v22, 3, v8
	v_readlane_b32 s16, v253, 48
	s_lshl_b64 s[4:5], s[96:97], 1
	v_readlane_b32 s26, v253, 58
	v_readlane_b32 s27, v253, 59
	s_add_u32 s4, s26, s4
	s_addc_u32 s5, s27, s5
	v_readlane_b32 s17, v253, 49
	v_readlane_b32 s18, v253, 50
	v_readlane_b32 s19, v253, 51
	v_readlane_b32 s20, v253, 52
	v_readlane_b32 s21, v253, 53
	v_readlane_b32 s22, v253, 54
	v_readlane_b32 s23, v253, 55
	v_readlane_b32 s24, v253, 56
	v_readlane_b32 s25, v253, 57
	v_readlane_b32 s28, v253, 60
	v_readlane_b32 s29, v253, 61
	v_readlane_b32 s30, v253, 62
	v_readlane_b32 s31, v253, 63
	s_waitcnt vmcnt(0)
	ds_write2_b32 v7, v0, v1 offset1:1
	ds_write2_b32 v7, v2, v3 offset0:2 offset1:3
	v_add_u32_e32 v0, 16, v6
	v_ashrrev_i32_e32 v1, 31, v0
	v_lshlrev_b64 v[0:1], 12, v[0:1]
	v_lshl_add_u64 v[0:1], v[4:5], 0, v[0:1]
	global_load_dwordx4 v[0:3], v[0:1], off
	s_waitcnt vmcnt(0)
	ds_write2_b32 v9, v0, v1 offset1:1
	v_add_u32_e32 v0, 0x1048, v7
	ds_write2_b32 v0, v2, v3 offset1:1
	v_add_u32_e32 v0, 32, v6
	v_ashrrev_i32_e32 v1, 31, v0
	v_lshlrev_b64 v[0:1], 12, v[0:1]
	v_lshl_add_u64 v[0:1], v[4:5], 0, v[0:1]
	global_load_dwordx4 v[0:3], v[0:1], off
	v_add_u32_e32 v9, 0x2080, v7
	s_waitcnt vmcnt(0)
	ds_write2_b32 v9, v0, v1 offset1:1
	v_add_u32_e32 v0, 0x2088, v7
	ds_write2_b32 v0, v2, v3 offset1:1
	v_add_u32_e32 v0, 48, v6
	v_ashrrev_i32_e32 v1, 31, v0
	v_lshlrev_b64 v[0:1], 12, v[0:1]
	v_lshl_add_u64 v[0:1], v[4:5], 0, v[0:1]
	global_load_dwordx4 v[0:3], v[0:1], off
	v_add_u32_e32 v4, 0x30c0, v7
	s_waitcnt vmcnt(0)
	ds_write2_b32 v4, v0, v1 offset1:1
	v_add_u32_e32 v0, 0x30c8, v7
	ds_write2_b32 v0, v2, v3 offset1:1
	v_lshlrev_b32_e32 v0, 3, v8
	v_and_b32_e32 v2, 56, v0
	v_lshlrev_b32_e32 v188, 1, v2
	v_mul_u32_u24_e32 v2, 0x104, v2
	v_lshl_add_u32 v2, v22, 2, v2
	s_waitcnt lgkmcnt(0)
	s_barrier
	ds_read2_b32 v[6:7], v2 offset1:32
	ds_read2_b32 v[8:9], v2 offset0:65 offset1:97
	ds_read2_b32 v[10:11], v2 offset0:130 offset1:162
	ds_read2_b32 v[12:13], v2 offset0:195 offset1:227
	v_add_u32_e32 v2, 0x400, v2
	ds_read2_b32 v[14:15], v2 offset0:4 offset1:36
	ds_read2_b32 v[16:17], v2 offset0:69 offset1:101
	ds_read2_b32 v[18:19], v2 offset0:134 offset1:166
	ds_read2_b32 v[20:21], v2 offset0:199 offset1:231
	v_add_u32_e32 v22, s2, v22
	v_ashrrev_i32_e32 v23, 31, v22
	v_lshl_add_u64 v[0:1], s[4:5], 0, v[188:189]
	v_lshlrev_b64 v[24:25], 13, v[22:23]
	s_waitcnt lgkmcnt(6)
	v_cvt_pk_bf16_f32 v2, v6, v8
	s_waitcnt lgkmcnt(4)
	v_cvt_pk_bf16_f32 v3, v10, v12
	s_waitcnt lgkmcnt(2)
	v_cvt_pk_bf16_f32 v4, v14, v16
	s_waitcnt lgkmcnt(0)
	v_cvt_pk_bf16_f32 v5, v18, v20
	v_lshl_add_u64 v[24:25], v[0:1], 0, v[24:25]
	v_add_u32_e32 v6, 32, v22
	global_store_dwordx4 v[24:25], v[2:5], off
	s_nop 1
	v_cvt_pk_bf16_f32 v2, v7, v9
	v_ashrrev_i32_e32 v7, 31, v6
	v_lshlrev_b64 v[6:7], 13, v[6:7]
	v_cvt_pk_bf16_f32 v3, v11, v13
	v_cvt_pk_bf16_f32 v4, v15, v17
	v_cvt_pk_bf16_f32 v5, v19, v21
	v_lshl_add_u64 v[0:1], v[0:1], 0, v[6:7]
	global_store_dwordx4 v[0:1], v[2:5], off

; DI int TID() { int t = threadIdx.x; asm volatile("" : "+v"(t)); return t; }
; template <bool MAP = false>
; DI void conv_tile(const float* __restrict__ src, int N, int K, bfu* __restrict__ dst, const float* __restrict__ g,
;                   int tk, int tn, char* smem, int ldk = -1) {
;   const int LK = ldk < 0 ? K : ldk;
;   float* T = (float*)smem;
;   const int tid = TID();
;   __syncthreads();
; #pragma unroll
;   for (int j = 0; j < 4; ++j) {
;     int k = (tid >> 4) + 16 * j, n4 = (tid & 15) * 4;
;     int gn = tn * 64 + n4, gk = tk * 64 + k;
;     float4 v = make_float4(0.f, 0.f, 0.f, 0.f);
;     const int og = MAP ? in_colmap(gn) : (gn < N ? gn : -1);
;     if (og >= 0) v = *(const float4*)(src + (size_t)gk * N + og);
;     float gg = g ? g[gk] : 1.f;
;     T[k * 65 + n4 + 0] = v.x * gg; T[k * 65 + n4 + 1] = v.y * gg; T[k * 65 + n4 + 2] = v.z * gg; T[k * 65 + n4 + 3] = v.w * gg;
;   }
;   __syncthreads();
; DI void conv_item_C(const Params& p, int L, int it, char* smem) {
;     ...
;   else if (it < 1536) { int t = it - 512; conv_tile(p.w_up + (size_t)L * D * DFF, DFF, D, p.wt_up, p.norm_mlp_g + L * D, t / 64, t % 64, smem); }
.LBB0_1935:
	s_andn2_b64 vcc, exec, s[2:3]
	s_cbranch_vccnz .LBB0_1945
	v_mov_b32_e32 v11, v224
	s_and_b32 s4, s12, 0x7c0
	s_lshl_b32 s2, s12, 6
	v_lshlrev_b32_e32 v0, 2, v11
	s_add_i32 s96, s4, 0xfffffe00
	v_ashrrev_i32_e32 v8, 4, v11
	v_and_b32_e32 v13, 60, v0
	s_and_b32 s84, s2, 0xfc0
	v_or_b32_e32 v0, s84, v13
	v_add_u32_e32 v6, s96, v8
	v_lshlrev_b32_e32 v188, 2, v0
	v_ashrrev_i32_e32 v7, 31, v6
	v_lshl_add_u64 v[4:5], s[90:91], 0, v[188:189]
	v_lshlrev_b64 v[0:1], 14, v[6:7]
	v_lshl_add_u64 v[0:1], v[4:5], 0, v[0:1]
	s_waitcnt vmcnt(63) expcnt(7) lgkmcnt(15)
	s_barrier
	v_add_u32_e32 v210, 16, v6
	v_ashrrev_i32_e32 v211, 31, v210
	v_lshlrev_b64 v[210:211], 14, v[210:211]
	v_lshl_add_u64 v[210:211], v[4:5], 0, v[210:211]
	global_load_dwordx4 v[240:243], v[210:211], off
	v_add_u32_e32 v210, 32, v6
	v_ashrrev_i32_e32 v211, 31, v210
	v_lshlrev_b64 v[210:211], 14, v[210:211]
	v_lshl_add_u64 v[210:211], v[4:5], 0, v[210:211]
	global_load_dwordx4 v[244:247], v[210:211], off
	v_add_u32_e32 v210, 48, v6
	v_ashrrev_i32_e32 v211, 31, v210
	v_lshlrev_b64 v[210:211], 14, v[210:211]
	v_lshl_add_u64 v[210:211], v[4:5], 0, v[210:211]
	global_load_dwordx4 v[248:251], v[210:211], off
	global_load_dwordx4 v[0:3], v[0:1], off
	v_readlane_b32 s16, v255, 6
	v_readlane_b32 s17, v255, 7
	v_mov_b32_e32 v10, 1.0
	s_andn2_b64 vcc, exec, s[16:17]
	v_cndmask_b32_e64 v9, 0, 1, s[16:17]
	v_cmp_ne_u32_e64 s[2:3], 1, v9
	v_mov_b32_e32 v12, 1.0
	s_cbranch_vccnz .LBB0_1938
	v_ashrrev_i32_e32 v9, 31, v8
	s_mov_b32 s5, s97
	v_lshl_add_u64 v[14:15], v[8:9], 0, s[4:5]
	v_lshl_add_u64 v[14:15], v[14:15], 2, s[94:95]
	global_load_dword v12, v[14:15], off offset:-2048

; DI int TID() { int t = threadIdx.x; asm volatile("" : "+v"(t)); return t; }
; DI unsigned pk2(float a, float b) { f32x2_t v = {a, b}; bf16x2_t r_ = __builtin_convertvector(v, bf16x2_t); return __builtin_bit_cast(unsigned, r_); }
; template <bool MAP = false>
; DI void conv_tile(const float* __restrict__ src, int N, int K, bfu* __restrict__ dst, const float* __restrict__ g,
;                   int tk, int tn, char* smem, int ldk = -1) {
;   const int LK = ldk < 0 ? K : ldk;
;   float* T = (float*)smem;
;   const int tid = TID();
;   __syncthreads();
; #pragma unroll
;   for (int j = 0; j < 4; ++j) {
;     int k = (tid >> 4) + 16 * j, n4 = (tid & 15) * 4;
;     int gn = tn * 64 + n4, gk = tk * 64 + k;
;     float4 v = make_float4(0.f, 0.f, 0.f, 0.f);
;     const int og = MAP ? in_colmap(gn) : (gn < N ? gn : -1);
;     if (og >= 0) v = *(const float4*)(src + (size_t)gk * N + og);
;     float gg = g ? g[gk] : 1.f;
;     T[k * 65 + n4 + 0] = v.x * gg; T[k * 65 + n4 + 1] = v.y * gg; T[k * 65 + n4 + 2] = v.z * gg; T[k * 65 + n4 + 3] = v.w * gg;
;   }
;   __syncthreads();
; #pragma unroll
;   for (int j = 0; j < 2; ++j) {
;     int n = (tid >> 3) + 32 * j, kc = tid & 7;
;     float e[8];
; #pragma unroll
;     for (int q = 0; q < 8; ++q) e[q] = T[(kc * 8 + q) * 65 + n];
;     u32x4 o = {pk2(e[0], e[1]), pk2(e[2], e[3]), pk2(e[4], e[5]), pk2(e[6], e[7])};
;     *(u32x4*)(dst + (size_t)(tn * 64 + n) * LK + tk * 64 + kc * 8) = o;
;   }
; }
; DI void conv_item_C(const Params& p, int L, int it, char* smem) {
;     ...
;   else if (it < 512) { int t = it - 256; conv_tile(p.w_o + (size_t)L * D * D, D, D, p.wt_o, nullptr, t / 16, t % 16, smem); }
.LBB0_1946:
	s_andn2_b64 vcc, exec, s[2:3]
	s_cbranch_vccnz .LBB0_1948
	v_mov_b32_e32 v8, v224
	s_lshl_b32 s3, s12, 2
	s_lshl_b32 s2, s12, 6
	v_lshlrev_b32_e32 v0, 2, v8
	s_and_b32 s3, s3, 0x7c0
	v_ashrrev_i32_e32 v2, 4, v8
	v_and_b32_e32 v3, 60, v0
	s_and_b32 s2, s2, 0x3c0
	s_add_i32 s96, s3, 0xfffffc00
	v_or_b32_e32 v0, s2, v3
	v_add_u32_e32 v6, s96, v2
	v_lshlrev_b32_e32 v188, 2, v0
	v_ashrrev_i32_e32 v7, 31, v6
	v_lshl_add_u64 v[4:5], s[52:53], 0, v[188:189]
	v_lshlrev_b64 v[0:1], 12, v[6:7]
	s_movk_i32 s3, 0x104
	v_lshl_add_u64 v[0:1], v[4:5], 0, v[0:1]
	v_mul_lo_u32 v2, v2, s3
	s_waitcnt vmcnt(63) expcnt(7) lgkmcnt(15)
	s_barrier
	v_lshl_add_u32 v7, v3, 2, v2
	v_add_u32_e32 v210, 16, v6
	v_ashrrev_i32_e32 v211, 31, v210
	v_lshlrev_b64 v[210:211], 12, v[210:211]
	v_lshl_add_u64 v[210:211], v[4:5], 0, v[210:211]
	global_load_dwordx4 v[240:243], v[210:211], off
	v_add_u32_e32 v210, 32, v6
	v_ashrrev_i32_e32 v211, 31, v210
	v_lshlrev_b64 v[210:211], 12, v[210:211]
	v_lshl_add_u64 v[210:211], v[4:5], 0, v[210:211]
	global_load_dwordx4 v[244:247], v[210:211], off
	v_add_u32_e32 v210, 48, v6
	v_ashrrev_i32_e32 v211, 31, v210
	v_lshlrev_b64 v[210:211], 12, v[210:211]
	v_lshl_add_u64 v[210:211], v[4:5], 0, v[210:211]
	global_load_dwordx4 v[248:251], v[210:211], off
	global_load_dwordx4 v[0:3], v[0:1], off
	v_add_u32_e32 v9, 0x1040, v7
	v_ashrrev_i32_e32 v22, 3, v8
	v_readlane_b32 s16, v253, 48
	s_lshl_b64 s[4:5], s[96:97], 1
	v_readlane_b32 s22, v253, 54
	v_readlane_b32 s23, v253, 55
	s_add_u32 s4, s22, s4
	s_addc_u32 s5, s23, s5
	v_readlane_b32 s17, v253, 49
	v_readlane_b32 s18, v253, 50
	v_readlane_b32 s19, v253, 51
	v_readlane_b32 s20, v253, 52
	v_readlane_b32 s21, v253, 53
	v_readlane_b32 s24, v253, 56
	v_readlane_b32 s25, v253, 57
	v_readlane_b32 s26, v253, 58
	v_readlane_b32 s27, v253, 59
	v_readlane_b32 s28, v253, 60
	v_readlane_b32 s29, v253, 61
	v_readlane_b32 s30, v253, 62
	v_readlane_b32 s31, v253, 63
	s_waitcnt vmcnt(0)
	ds_write2_b32 v7, v0, v1 offset1:1
	ds_write2_b32 v7, v2, v3 offset0:2 offset1:3
	v_add_u32_e32 v0, 16, v6
	v_ashrrev_i32_e32 v1, 31, v0
	v_lshlrev_b64 v[0:1], 12, v[0:1]
	v_lshl_add_u64 v[0:1], v[4:5], 0, v[0:1]
	global_load_dwordx4 v[0:3], v[0:1], off
	s_waitcnt vmcnt(0)
	ds_write2_b32 v9, v0, v1 offset1:1
	v_add_u32_e32 v0, 0x1048, v7
	ds_write2_b32 v0, v2, v3 offset1:1
	v_add_u32_e32 v0, 32, v6
	v_ashrrev_i32_e32 v1, 31, v0
	v_lshlrev_b64 v[0:1], 12, v[0:1]
	v_lshl_add_u64 v[0:1], v[4:5], 0, v[0:1]
	global_load_dwordx4 v[0:3], v[0:1], off
	v_add_u32_e32 v9, 0x2080, v7
	s_waitcnt vmcnt(0)
	ds_write2_b32 v9, v0, v1 offset1:1
	v_add_u32_e32 v0, 0x2088, v7
	ds_write2_b32 v0, v2, v3 offset1:1
	v_add_u32_e32 v0, 48, v6
	v_ashrrev_i32_e32 v1, 31, v0
	v_lshlrev_b64 v[0:1], 12, v[0:1]
	v_lshl_add_u64 v[0:1], v[4:5], 0, v[0:1]
	global_load_dwordx4 v[0:3], v[0:1], off
	v_add_u32_e32 v4, 0x30c0, v7
	s_waitcnt vmcnt(0)
	ds_write2_b32 v4, v0, v1 offset1:1
	v_add_u32_e32 v0, 0x30c8, v7
	ds_write2_b32 v0, v2, v3 offset1:1
	v_lshlrev_b32_e32 v0, 3, v8
	v_and_b32_e32 v2, 56, v0
	v_lshlrev_b32_e32 v188, 1, v2
	v_mul_u32_u24_e32 v2, 0x104, v2
	v_lshl_add_u32 v2, v22, 2, v2
	s_waitcnt lgkmcnt(0)
	s_barrier
	ds_read2_b32 v[6:7], v2 offset1:32
	ds_read2_b32 v[8:9], v2 offset0:65 offset1:97
	ds_read2_b32 v[10:11], v2 offset0:130 offset1:162
	ds_read2_b32 v[12:13], v2 offset0:195 offset1:227
	v_add_u32_e32 v2, 0x400, v2
	ds_read2_b32 v[14:15], v2 offset0:4 offset1:36
	ds_read2_b32 v[16:17], v2 offset0:69 offset1:101
	ds_read2_b32 v[18:19], v2 offset0:134 offset1:166
	ds_read2_b32 v[20:21], v2 offset0:199 offset1:231
	v_add_u32_e32 v22, s2, v22
	v_ashrrev_i32_e32 v23, 31, v22
	v_lshl_add_u64 v[0:1], s[4:5], 0, v[188:189]
	v_lshlrev_b64 v[24:25], 11, v[22:23]
	s_waitcnt lgkmcnt(6)
	v_cvt_pk_bf16_f32 v2, v6, v8
	s_waitcnt lgkmcnt(4)
	v_cvt_pk_bf16_f32 v3, v10, v12
	s_waitcnt lgkmcnt(2)
	v_cvt_pk_bf16_f32 v4, v14, v16
	s_waitcnt lgkmcnt(0)
	v_cvt_pk_bf16_f32 v5, v18, v20
	v_lshl_add_u64 v[24:25], v[0:1], 0, v[24:25]
	v_add_u32_e32 v6, 32, v22
	global_store_dwordx4 v[24:25], v[2:5], off
	s_nop 1
	v_cvt_pk_bf16_f32 v2, v7, v9
	v_ashrrev_i32_e32 v7, 31, v6
	v_lshlrev_b64 v[6:7], 11, v[6:7]
	v_cvt_pk_bf16_f32 v3, v11, v13
	v_cvt_pk_bf16_f32 v4, v15, v17
	v_cvt_pk_bf16_f32 v5, v19, v21
	v_lshl_add_u64 v[0:1], v[0:1], 0, v[6:7]
	global_store_dwordx4 v[0:1], v[2:5], off

; DI int TID() { int t = threadIdx.x; asm volatile("" : "+v"(t)); return t; }
; DI unsigned pk2(float a, float b) { f32x2_t v = {a, b}; bf16x2_t r_ = __builtin_convertvector(v, bf16x2_t); return __builtin_bit_cast(unsigned, r_); }
; template <bool MAP = false>
; DI void conv_tile(const float* __restrict__ src, int N, int K, bfu* __restrict__ dst, const float* __restrict__ g,
;                   int tk, int tn, char* smem, int ldk = -1) {
;   const int LK = ldk < 0 ? K : ldk;
;   float* T = (float*)smem;
;   const int tid = TID();
;   __syncthreads();
; #pragma unroll
;   for (int j = 0; j < 4; ++j) {
;     int k = (tid >> 4) + 16 * j, n4 = (tid & 15) * 4;
;     int gn = tn * 64 + n4, gk = tk * 64 + k;
;     float4 v = make_float4(0.f, 0.f, 0.f, 0.f);
;     const int og = MAP ? in_colmap(gn) : (gn < N ? gn : -1);
;     if (og >= 0) v = *(const float4*)(src + (size_t)gk * N + og);
;     float gg = g ? g[gk] : 1.f;
;     T[k * 65 + n4 + 0] = v.x * gg; T[k * 65 + n4 + 1] = v.y * gg; T[k * 65 + n4 + 2] = v.z * gg; T[k * 65 + n4 + 3] = v.w * gg;
;   }
;   __syncthreads();
; #pragma unroll
;   for (int j = 0; j < 2; ++j) {
;     int n = (tid >> 3) + 32 * j, kc = tid & 7;
;     float e[8];
; #pragma unroll
;     for (int q = 0; q < 8; ++q) e[q] = T[(kc * 8 + q) * 65 + n];
;     u32x4 o = {pk2(e[0], e[1]), pk2(e[2], e[3]), pk2(e[4], e[5]), pk2(e[6], e[7])};
;     *(u32x4*)(dst + (size_t)(tn * 64 + n) * LK + tk * 64 + kc * 8) = o;
;   }
; DI void conv_item_C(const Params& p, int L, int it, char* smem) {
;   if (it < 256) { int t = it; int n = t >> 6; t &= 63; conv_tile(p.w_branch + ((size_t)L * 4 + n) * 256 * D, D, 256, p.wt_br + (size_t)n * 256, nullptr, t / 16, t % 16, smem, 1024); }
.LBB0_1949:
	s_andn2_b64 vcc, exec, s[2:3]
	s_cbranch_vccnz .LBB0_1951
	s_lshr_b32 s96, s12, 6
	s_lshl_b64 s[2:3], s[96:97], 20
	s_add_u32 s4, s89, s2
	v_readlane_b32 s2, v255, 31
	v_readlane_b32 s16, v253, 48
	s_addc_u32 s5, s2, s3
	s_lshl_b64 s[2:3], s[96:97], 9
	v_readlane_b32 s20, v253, 52
	v_readlane_b32 s21, v253, 53
	s_add_u32 s20, s20, s2
	v_mov_b32_e32 v8, v224
	s_addc_u32 s3, s21, s3
	s_lshl_b32 s2, s12, 6
	v_lshlrev_b32_e32 v0, 2, v8
	s_lshl_b32 s12, s12, 2
	v_ashrrev_i32_e32 v2, 4, v8
	v_and_b32_e32 v3, 60, v0
	s_and_b32 s2, s2, 0x3c0
	s_and_b32 s12, s12, 0xc0
	v_or_b32_e32 v0, s2, v3
	v_add_u32_e32 v6, s12, v2
	v_lshlrev_b32_e32 v188, 2, v0
	v_ashrrev_i32_e32 v7, 31, v6
	v_lshl_add_u64 v[4:5], s[4:5], 0, v[188:189]
	v_lshlrev_b64 v[0:1], 12, v[6:7]
	s_movk_i32 s4, 0x104
	v_lshl_add_u64 v[0:1], v[4:5], 0, v[0:1]
	v_mul_lo_u32 v2, v2, s4
	s_waitcnt vmcnt(63) expcnt(7) lgkmcnt(15)
	s_barrier
	v_lshl_add_u32 v7, v3, 2, v2
	v_add_u32_e32 v210, 16, v6
	v_ashrrev_i32_e32 v211, 31, v210
	v_lshlrev_b64 v[210:211], 12, v[210:211]
	v_lshl_add_u64 v[210:211], v[4:5], 0, v[210:211]
	global_load_dwordx4 v[240:243], v[210:211], off
	v_add_u32_e32 v210, 32, v6
	v_ashrrev_i32_e32 v211, 31, v210
	v_lshlrev_b64 v[210:211], 12, v[210:211]
	v_lshl_add_u64 v[210:211], v[4:5], 0, v[210:211]
	global_load_dwordx4 v[244:247], v[210:211], off
	v_add_u32_e32 v210, 48, v6
	v_ashrrev_i32_e32 v211, 31, v210
	v_lshlrev_b64 v[210:211], 12, v[210:211]
	v_lshl_add_u64 v[210:211], v[4:5], 0, v[210:211]
	global_load_dwordx4 v[248:251], v[210:211], off
	global_load_dwordx4 v[0:3], v[0:1], off
	v_add_u32_e32 v9, 0x1040, v7
	v_ashrrev_i32_e32 v22, 3, v8
	s_lshl_b32 s4, s12, 1
	s_add_u32 s4, s20, s4
	s_addc_u32 s5, s3, 0
	v_readlane_b32 s17, v253, 49
	v_readlane_b32 s18, v253, 50
	v_readlane_b32 s19, v253, 51
	v_readlane_b32 s22, v253, 54
	v_readlane_b32 s23, v253, 55
	v_readlane_b32 s24, v253, 56
	v_readlane_b32 s25, v253, 57
	v_readlane_b32 s26, v253, 58
	v_readlane_b32 s27, v253, 59
	v_readlane_b32 s28, v253, 60
	v_readlane_b32 s29, v253, 61
	v_readlane_b32 s30, v253, 62
	v_readlane_b32 s31, v253, 63
	s_waitcnt vmcnt(0)
	ds_write2_b32 v7, v0, v1 offset1:1
	ds_write2_b32 v7, v2, v3 offset0:2 offset1:3
	v_add_u32_e32 v0, 16, v6
	v_ashrrev_i32_e32 v1, 31, v0
	v_lshlrev_b64 v[0:1], 12, v[0:1]
	v_lshl_add_u64 v[0:1], v[4:5], 0, v[0:1]
	global_load_dwordx4 v[0:3], v[0:1], off
	s_waitcnt vmcnt(0)
	ds_write2_b32 v9, v0, v1 offset1:1
	v_add_u32_e32 v0, 0x1048, v7
	ds_write2_b32 v0, v2, v3 offset1:1
	v_add_u32_e32 v0, 32, v6
	v_ashrrev_i32_e32 v1, 31, v0
	v_lshlrev_b64 v[0:1], 12, v[0:1]
	v_lshl_add_u64 v[0:1], v[4:5], 0, v[0:1]
	global_load_dwordx4 v[0:3], v[0:1], off
	v_add_u32_e32 v9, 0x2080, v7
	s_waitcnt vmcnt(0)
	ds_write2_b32 v9, v0, v1 offset1:1
	v_add_u32_e32 v0, 0x2088, v7
	ds_write2_b32 v0, v2, v3 offset1:1
	v_add_u32_e32 v0, 48, v6
	v_ashrrev_i32_e32 v1, 31, v0
	v_lshlrev_b64 v[0:1], 12, v[0:1]
	v_lshl_add_u64 v[0:1], v[4:5], 0, v[0:1]
	global_load_dwordx4 v[0:3], v[0:1], off
	v_add_u32_e32 v4, 0x30c0, v7
	s_waitcnt vmcnt(0)
	ds_write2_b32 v4, v0, v1 offset1:1
	v_add_u32_e32 v0, 0x30c8, v7
	ds_write2_b32 v0, v2, v3 offset1:1
	v_lshlrev_b32_e32 v0, 3, v8
	v_and_b32_e32 v2, 56, v0
	v_lshlrev_b32_e32 v188, 1, v2
	v_mul_u32_u24_e32 v2, 0x104, v2
	v_lshl_add_u32 v2, v22, 2, v2
	s_waitcnt lgkmcnt(0)
	s_barrier
	ds_read2_b32 v[6:7], v2 offset1:32
	ds_read2_b32 v[8:9], v2 offset0:65 offset1:97
	ds_read2_b32 v[10:11], v2 offset0:130 offset1:162
	ds_read2_b32 v[12:13], v2 offset0:195 offset1:227
	v_add_u32_e32 v2, 0x400, v2
	ds_read2_b32 v[14:15], v2 offset0:4 offset1:36
	ds_read2_b32 v[16:17], v2 offset0:69 offset1:101
	ds_read2_b32 v[18:19], v2 offset0:134 offset1:166
	ds_read2_b32 v[20:21], v2 offset0:199 offset1:231
	v_add_u32_e32 v22, s2, v22
	v_ashrrev_i32_e32 v23, 31, v22
	v_lshl_add_u64 v[0:1], s[4:5], 0, v[188:189]
	v_lshlrev_b64 v[24:25], 11, v[22:23]
	s_waitcnt lgkmcnt(6)
	v_cvt_pk_bf16_f32 v2, v6, v8
	s_waitcnt lgkmcnt(4)
	v_cvt_pk_bf16_f32 v3, v10, v12
	s_waitcnt lgkmcnt(2)
	v_cvt_pk_bf16_f32 v4, v14, v16
	s_waitcnt lgkmcnt(0)
	v_cvt_pk_bf16_f32 v5, v18, v20
	v_lshl_add_u64 v[24:25], v[0:1], 0, v[24:25]
	v_add_u32_e32 v6, 32, v22
	global_store_dwordx4 v[24:25], v[2:5], off
	s_nop 1
	v_cvt_pk_bf16_f32 v2, v7, v9
	v_ashrrev_i32_e32 v7, 31, v6
	v_lshlrev_b64 v[6:7], 11, v[6:7]
	v_cvt_pk_bf16_f32 v3, v11, v13
	v_cvt_pk_bf16_f32 v4, v15, v17
	v_cvt_pk_bf16_f32 v5, v19, v21
	v_lshl_add_u64 v[0:1], v[0:1], 0, v[6:7]
	global_store_dwordx4 v[0:1], v[2:5], off

; DI int TID() { int t = threadIdx.x; asm volatile("" : "+v"(t)); return t; }
; template <bool MAP = false>
; DI void conv_tile(const float* __restrict__ src, int N, int K, bfu* __restrict__ dst, const float* __restrict__ g,
;                   int tk, int tn, char* smem, int ldk = -1) {
;   const int LK = ldk < 0 ? K : ldk;
;   float* T = (float*)smem;
;   const int tid = TID();
;   __syncthreads();
; #pragma unroll
;   for (int j = 0; j < 4; ++j) {
;     int k = (tid >> 4) + 16 * j, n4 = (tid & 15) * 4;
;     int gn = tn * 64 + n4, gk = tk * 64 + k;
;     float4 v = make_float4(0.f, 0.f, 0.f, 0.f);
;     const int og = MAP ? in_colmap(gn) : (gn < N ? gn : -1);
;     if (og >= 0) v = *(const float4*)(src + (size_t)gk * N + og);
;     float gg = g ? g[gk] : 1.f;
;     T[k * 65 + n4 + 0] = v.x * gg; T[k * 65 + n4 + 1] = v.y * gg; T[k * 65 + n4 + 2] = v.z * gg; T[k * 65 + n4 + 3] = v.w * gg;
;   }
;   __syncthreads();
; DI void conv_item_B(const Params& p, int L, int it, char* smem) {
;     ...
;   else if (it < 52) { int t = it - 36; conv_tile(p.mla_w_ukv + (size_t)L * 128 * 512, 512, 128, p.wt_ukv, p.mla_ckv_g + L * 128, t / 8, t % 8, smem); }
.LBB0_1972:
	s_add_i32 s2, s33, 0xfffff91c
	v_mov_b32_e32 v11, v224
	s_lshl_b32 s3, s2, 6
	v_lshlrev_b32_e32 v0, 2, v11
	s_lshl_b32 s2, s2, 3
	v_ashrrev_i32_e32 v13, 4, v11
	v_and_b32_e32 v14, 60, v0
	s_and_b32 s4, s3, 0x1c0
	s_and_b32 s5, s2, 0x7fffffc0
	v_or_b32_e32 v0, s4, v14
	v_add_u32_e32 v8, s5, v13
	v_lshlrev_b32_e32 v188, 2, v0
	v_ashrrev_i32_e32 v9, 31, v8
	v_lshl_add_u64 v[6:7], s[8:9], 0, v[188:189]
	v_lshlrev_b64 v[0:1], 11, v[8:9]
	v_lshl_add_u64 v[0:1], v[6:7], 0, v[0:1]
	s_waitcnt vmcnt(63) expcnt(7) lgkmcnt(15)
	s_barrier
	v_add_u32_e32 v210, 16, v8
	v_ashrrev_i32_e32 v211, 31, v210
	v_lshlrev_b64 v[210:211], 11, v[210:211]
	v_lshl_add_u64 v[210:211], v[6:7], 0, v[210:211]
	global_load_dwordx4 v[240:243], v[210:211], off
	v_add_u32_e32 v210, 32, v8
	v_ashrrev_i32_e32 v211, 31, v210
	v_lshlrev_b64 v[210:211], 11, v[210:211]
	v_lshl_add_u64 v[210:211], v[6:7], 0, v[210:211]
	global_load_dwordx4 v[244:247], v[210:211], off
	v_add_u32_e32 v210, 48, v8
	v_ashrrev_i32_e32 v211, 31, v210
	v_lshlrev_b64 v[210:211], 11, v[210:211]
	v_lshl_add_u64 v[210:211], v[6:7], 0, v[210:211]
	global_load_dwordx4 v[248:251], v[210:211], off
	global_load_dwordx4 v[0:3], v[0:1], off
	v_readlane_b32 s16, v254, 42
	v_readlane_b32 s17, v254, 43
	v_mov_b32_e32 v10, 1.0
	s_andn2_b64 vcc, exec, s[16:17]
	v_cndmask_b32_e64 v4, 0, 1, s[16:17]
	v_cmp_ne_u32_e64 s[2:3], 1, v4
	v_lshl_add_u64 v[4:5], v[8:9], 2, s[10:11]
	v_mov_b32_e32 v12, 1.0
	s_cbranch_vccnz .LBB0_1974
	global_load_dword v12, v[4:5], off
